# SwiGLU hidden-activation stores without the nt hint
# speedup vs baseline: 1.0109x; 1.0023x over previous
.LBB0_161:
	s_lshl_b32 s5, s12, 8
	v_mov_b32_e32 v82, v159
	v_mov_b32_e32 v83, v1
	s_add_i32 s5, s5, s31
	s_nop 0
	v_add_u32_e32 v182, s5, v82
	s_lshl_b32 s5, s42, 7
	s_or_b32 s5, s5, s34
	v_lshl_add_u32 v186, v83, 3, s5
	s_ashr_i32 s5, s12, 5
	s_mul_hi_i32 s7, s5, 0x5800
	s_mulk_i32 s5, 0x5800
	s_add_u32 s14, s28, s5
	s_addc_u32 s15, s29, s7
	v_ashrrev_i32_e32 v187, 31, v186
	v_lshl_add_u64 v[86:87], v[186:187], 2, s[14:15]
	s_mov_b64 s[14:15], 0x2c00
	s_movk_i32 s5, 0x2000
	global_load_dwordx4 v[82:85], v[86:87], off offset:16
	global_load_dwordx4 v[98:101], v[86:87], off
	v_lshl_add_u64 v[88:89], v[86:87], 0, s[14:15]
	v_add_co_u32_e32 v86, vcc, s5, v86
	v_ashrrev_i32_e32 v183, 31, v182
	s_nop 0
	v_addc_co_u32_e32 v87, vcc, 0, v87, vcc
	v_lshl_add_u64 v[160:161], v[182:183], 2, s[0:1]
	global_load_dwordx4 v[102:105], v[86:87], off offset:3072
	s_nop 0
	global_load_dwordx4 v[86:89], v[88:89], off offset:16
	v_add_u32_e32 v187, 16, v182
	global_load_dword v184, v[160:161], off
	global_load_dword v180, v[160:161], off offset:64
	global_load_dword v178, v[160:161], off offset:128
	global_load_dword v176, v[160:161], off offset:192
	global_load_dword v174, v[160:161], off offset:512
	global_load_dword v172, v[160:161], off offset:576
	global_load_dword v175, v[160:161], off offset:640
	global_load_dword v160, v[160:161], off offset:704
	v_add_u32_e32 v185, 32, v182
	v_add_u32_e32 v183, 48, v182
	v_add_u32_e32 v181, 0x80, v182
	v_add_u32_e32 v179, 0x90, v182
	v_add_u32_e32 v177, 0xa0, v182
	s_waitcnt vmcnt(0)
	v_fmamk_f32 v158, v184, 0x3a800000, v223
	v_cmp_gt_f32_e32 vcc, s95, v158
	v_mul_f32_e32 v168, 0x4b800000, v158
	s_nop 0
	v_cndmask_b32_e32 v158, v158, v168, vcc
	v_rsq_f32_e32 v158, v158
	s_nop 0
	v_mul_f32_e32 v168, 0x45800000, v158
	v_cndmask_b32_e32 v184, v158, v168, vcc
	v_fmamk_f32 v158, v180, 0x3a800000, v223
	v_cmp_gt_f32_e32 vcc, s95, v158
	v_mul_f32_e32 v168, 0x4b800000, v158
	s_nop 0
	v_cndmask_b32_e32 v158, v158, v168, vcc
	v_rsq_f32_e32 v158, v158
	s_nop 0
	v_mul_f32_e32 v168, 0x45800000, v158
	v_cndmask_b32_e32 v180, v158, v168, vcc
	v_fmamk_f32 v158, v178, 0x3a800000, v223
	v_cmp_gt_f32_e32 vcc, s95, v158
	v_mul_f32_e32 v168, 0x4b800000, v158
	s_nop 0
	v_cndmask_b32_e32 v158, v158, v168, vcc
	v_rsq_f32_e32 v158, v158
	s_nop 0
	v_mul_f32_e32 v168, 0x45800000, v158
	v_cndmask_b32_e32 v178, v158, v168, vcc
	v_fmamk_f32 v158, v176, 0x3a800000, v223
	v_cmp_gt_f32_e32 vcc, s95, v158
	v_mul_f32_e32 v168, 0x4b800000, v158
	s_nop 0
	v_cndmask_b32_e32 v158, v158, v168, vcc
	v_rsq_f32_e32 v158, v158
	s_nop 0
	v_mul_f32_e32 v168, 0x45800000, v158
	v_cndmask_b32_e32 v176, v158, v168, vcc
	v_fmamk_f32 v158, v174, 0x3a800000, v223
	v_cmp_gt_f32_e32 vcc, s95, v158
	v_mul_f32_e32 v168, 0x4b800000, v158
	s_nop 0
	v_cndmask_b32_e32 v158, v158, v168, vcc
	v_rsq_f32_e32 v158, v158
	s_nop 0
	v_mul_f32_e32 v168, 0x45800000, v158
	v_cndmask_b32_e32 v174, v158, v168, vcc
	v_fmamk_f32 v158, v172, 0x3a800000, v223
	v_cmp_gt_f32_e32 vcc, s95, v158
	v_mul_f32_e32 v168, 0x4b800000, v158
	s_nop 0
	v_cndmask_b32_e32 v158, v158, v168, vcc
	v_rsq_f32_e32 v158, v158
	s_nop 0
	v_mul_f32_e32 v168, 0x45800000, v158
	v_cndmask_b32_e32 v172, v158, v168, vcc
	v_fmamk_f32 v158, v175, 0x3a800000, v223
	v_add_u32_e32 v175, 0xb0, v182
	v_cmp_gt_f32_e32 vcc, s95, v158
	v_mul_f32_e32 v168, 0x4b800000, v158
	v_fmamk_f32 v160, v160, 0x3a800000, v223
	v_cndmask_b32_e32 v158, v158, v168, vcc
	v_rsq_f32_e32 v158, v158
	v_mul_f32_e32 v161, 0x4b800000, v160
	v_mul_f32_e32 v168, 0x45800000, v158
	v_cndmask_b32_e32 v158, v158, v168, vcc
	v_cmp_gt_f32_e32 vcc, s95, v160
	s_nop 1
	v_cndmask_b32_e32 v160, v160, v161, vcc
	v_rsq_f32_e32 v160, v160
	s_nop 0
	v_mul_f32_e32 v161, 0x45800000, v160
	v_cndmask_b32_e32 v160, v160, v161, vcc
	v_ashrrev_i32_e32 v161, 6, v186
	v_and_b32_e32 v186, 56, v186
	v_pk_fma_f32 v[138:139], v[138:139], v[184:185], v[98:99] op_sel_hi:[1,0,1]
	v_pk_fma_f32 v[142:143], v[142:143], v[184:185], v[102:103] op_sel_hi:[1,0,1]
	v_mul_f32_e32 v168, 0xbfb8aa3b, v138
	v_mul_f32_e32 v169, 0xbfb8aa3b, v139
	v_exp_f32_e32 v168, v168
	v_exp_f32_e32 v169, v169
	v_pk_fma_f32 v[140:141], v[140:141], v[184:185], v[100:101] op_sel_hi:[1,0,1]
	v_pk_fma_f32 v[134:135], v[134:135], v[184:185], v[82:83] op_sel_hi:[1,0,1]
	v_add_f32_e32 v168, 1.0, v168
	v_add_f32_e32 v169, 1.0, v169
	v_rcp_f32_e32 v168, v168
	v_rcp_f32_e32 v169, v169
	v_pk_fma_f32 v[130:131], v[130:131], v[184:185], v[86:87] op_sel_hi:[1,0,1]
	v_pk_fma_f32 v[132:133], v[132:133], v[184:185], v[88:89] op_sel_hi:[1,0,1]
	v_readlane_b32 s14, v254, 27
	v_pk_mul_f32 v[138:139], v[138:139], v[168:169]
	v_readlane_b32 s15, v254, 28
	v_pk_mul_f32 v[138:139], v[142:143], v[138:139]
	v_pk_fma_f32 v[142:143], v[144:145], v[184:185], v[104:105] op_sel_hi:[1,0,1]
	v_mul_f32_e32 v144, 0xbfb8aa3b, v140
	v_mul_f32_e32 v145, 0xbfb8aa3b, v141
	v_exp_f32_e32 v144, v144
	v_exp_f32_e32 v145, v145
	v_add_f32_e32 v144, 1.0, v144
	v_add_f32_e32 v145, 1.0, v145
	v_rcp_f32_e32 v144, v144
	v_rcp_f32_e32 v145, v145
	s_nop 0
	v_pk_mul_f32 v[140:141], v[140:141], v[144:145]
	s_nop 0
	v_pk_mul_f32 v[140:141], v[142:143], v[140:141]
	v_mul_f32_e32 v142, 0xbfb8aa3b, v134
	v_mul_f32_e32 v143, 0xbfb8aa3b, v135
	v_exp_f32_e32 v142, v142
	v_exp_f32_e32 v143, v143
	v_add_f32_e32 v142, 1.0, v142
	v_add_f32_e32 v143, 1.0, v143
	v_rcp_f32_e32 v142, v142
	v_rcp_f32_e32 v143, v143
	s_nop 0
	v_pk_mul_f32 v[134:135], v[134:135], v[142:143]
	s_nop 0
	v_pk_mul_f32 v[130:131], v[130:131], v[134:135]
	v_pk_fma_f32 v[134:135], v[136:137], v[184:185], v[84:85] op_sel_hi:[1,0,1]
	s_nop 0
	v_mul_f32_e32 v136, 0xbfb8aa3b, v134
	v_mul_f32_e32 v137, 0xbfb8aa3b, v135
	v_exp_f32_e32 v136, v136
	v_exp_f32_e32 v137, v137
	v_add_f32_e32 v136, 1.0, v136
	v_add_f32_e32 v137, 1.0, v137
	v_rcp_f32_e32 v136, v136
	v_rcp_f32_e32 v137, v137
	s_nop 0
	v_pk_mul_f32 v[134:135], v[134:135], v[136:137]
	s_nop 0
	v_pk_mul_f32 v[136:137], v[132:133], v[134:135]
	v_cvt_pk_bf16_f32 v134, v130, v131
	v_lshrrev_b32_e32 v130, 8, v182
	v_mad_i32_i24 v130, v130, 44, v161
	v_ashrrev_i32_e32 v131, 31, v130
	v_cvt_pk_bf16_f32 v135, v136, v137
	v_lshlrev_b64 v[130:131], 15, v[130:131]
	v_lshlrev_b32_e32 v136, 7, v182
	v_lshl_add_u64 v[130:131], s[14:15], 0, v[130:131]
	v_and_b32_e32 v136, 0x7f80, v136
	v_mov_b32_e32 v137, v0
	v_lshl_add_u64 v[136:137], v[130:131], 0, v[136:137]
	v_lshlrev_b32_e32 v130, 1, v186
	v_mov_b32_e32 v131, v0
	v_cvt_pk_bf16_f32 v132, v138, v139
	v_cvt_pk_bf16_f32 v133, v140, v141
	v_lshl_add_u64 v[136:137], v[136:137], 0, v[130:131]
	global_store_dwordx4 v[136:137], v[132:135], off
	v_pk_fma_f32 v[126:127], v[126:127], v[180:181], v[98:99] op_sel_hi:[1,0,1]
	v_pk_fma_f32 v[122:123], v[122:123], v[180:181], v[102:103] op_sel_hi:[1,0,1]
	v_mul_f32_e32 v132, 0xbfb8aa3b, v126
	v_mul_f32_e32 v133, 0xbfb8aa3b, v127
	v_exp_f32_e32 v132, v132
	v_exp_f32_e32 v133, v133
	v_pk_fma_f32 v[124:125], v[124:125], v[180:181], v[104:105] op_sel_hi:[1,0,1]
	v_pk_fma_f32 v[118:119], v[118:119], v[180:181], v[82:83] op_sel_hi:[1,0,1]
	v_add_f32_e32 v132, 1.0, v132
	v_add_f32_e32 v133, 1.0, v133
	v_rcp_f32_e32 v132, v132
	v_rcp_f32_e32 v133, v133
	v_pk_fma_f32 v[114:115], v[114:115], v[180:181], v[86:87] op_sel_hi:[1,0,1]
	v_pk_fma_f32 v[116:117], v[116:117], v[180:181], v[88:89] op_sel_hi:[1,0,1]
	v_pk_mul_f32 v[126:127], v[126:127], v[132:133]
	s_nop 0
	v_pk_mul_f32 v[122:123], v[122:123], v[126:127]
	v_pk_fma_f32 v[126:127], v[128:129], v[180:181], v[100:101] op_sel_hi:[1,0,1]
	s_nop 0
	v_mul_f32_e32 v128, 0xbfb8aa3b, v126
	v_mul_f32_e32 v129, 0xbfb8aa3b, v127
	v_exp_f32_e32 v128, v128
	v_exp_f32_e32 v129, v129
	v_add_f32_e32 v128, 1.0, v128
	v_add_f32_e32 v129, 1.0, v129
	v_rcp_f32_e32 v128, v128
	v_rcp_f32_e32 v129, v129
	s_nop 0
	v_pk_mul_f32 v[126:127], v[126:127], v[128:129]
	s_nop 0
	v_pk_mul_f32 v[124:125], v[124:125], v[126:127]
	v_mul_f32_e32 v126, 0xbfb8aa3b, v118
	v_mul_f32_e32 v127, 0xbfb8aa3b, v119
	v_exp_f32_e32 v126, v126
	v_exp_f32_e32 v127, v127
	v_add_f32_e32 v126, 1.0, v126
	v_add_f32_e32 v127, 1.0, v127
	v_rcp_f32_e32 v126, v126
	v_rcp_f32_e32 v127, v127
	s_nop 0
	v_pk_mul_f32 v[118:119], v[118:119], v[126:127]
	s_nop 0
	v_pk_mul_f32 v[118:119], v[114:115], v[118:119]
	v_pk_fma_f32 v[114:115], v[120:121], v[180:181], v[84:85] op_sel_hi:[1,0,1]
	s_nop 0
	v_mul_f32_e32 v120, 0xbfb8aa3b, v114
	v_mul_f32_e32 v121, 0xbfb8aa3b, v115
	v_exp_f32_e32 v120, v120
	v_exp_f32_e32 v121, v121
	v_add_f32_e32 v120, 1.0, v120
	v_add_f32_e32 v121, 1.0, v121
	v_rcp_f32_e32 v120, v120
	v_rcp_f32_e32 v121, v121
	s_nop 0
	v_pk_mul_f32 v[114:115], v[114:115], v[120:121]
	s_nop 0
	v_pk_mul_f32 v[120:121], v[116:117], v[114:115]
	v_cvt_pk_bf16_f32 v116, v118, v119
	v_lshrrev_b32_e32 v118, 8, v187
	v_mad_i32_i24 v118, v118, 44, v161
	v_ashrrev_i32_e32 v119, 31, v118
	v_cvt_pk_bf16_f32 v117, v120, v121
	v_lshlrev_b64 v[118:119], 15, v[118:119]
	v_lshlrev_b32_e32 v120, 7, v187
	v_lshl_add_u64 v[118:119], s[14:15], 0, v[118:119]
	v_and_b32_e32 v120, 0x7f80, v120
	v_mov_b32_e32 v121, v0
	v_lshl_add_u64 v[118:119], v[118:119], 0, v[120:121]
	v_cvt_pk_bf16_f32 v114, v122, v123
	v_cvt_pk_bf16_f32 v115, v124, v125
	v_lshl_add_u64 v[118:119], v[118:119], 0, v[130:131]
	global_store_dwordx4 v[118:119], v[114:117], off
	v_pk_fma_f32 v[110:111], v[110:111], v[178:179], v[98:99] op_sel_hi:[1,0,1]
	v_pk_fma_f32 v[106:107], v[106:107], v[178:179], v[102:103] op_sel_hi:[1,0,1]
	v_mul_f32_e32 v114, 0xbfb8aa3b, v110
	v_mul_f32_e32 v115, 0xbfb8aa3b, v111
	v_exp_f32_e32 v114, v114
	v_exp_f32_e32 v115, v115
	v_pk_fma_f32 v[108:109], v[108:109], v[178:179], v[104:105] op_sel_hi:[1,0,1]
	v_pk_fma_f32 v[94:95], v[94:95], v[178:179], v[82:83] op_sel_hi:[1,0,1]
	v_add_f32_e32 v114, 1.0, v114
	v_add_f32_e32 v115, 1.0, v115
	v_rcp_f32_e32 v114, v114
	v_rcp_f32_e32 v115, v115
	v_pk_fma_f32 v[90:91], v[90:91], v[178:179], v[86:87] op_sel_hi:[1,0,1]
	v_pk_fma_f32 v[92:93], v[92:93], v[178:179], v[88:89] op_sel_hi:[1,0,1]
	v_pk_mul_f32 v[110:111], v[110:111], v[114:115]
	s_nop 0
	v_pk_mul_f32 v[106:107], v[106:107], v[110:111]
	v_pk_fma_f32 v[110:111], v[112:113], v[178:179], v[100:101] op_sel_hi:[1,0,1]
	s_nop 0
	v_mul_f32_e32 v112, 0xbfb8aa3b, v110
	v_mul_f32_e32 v113, 0xbfb8aa3b, v111
	v_exp_f32_e32 v112, v112
	v_exp_f32_e32 v113, v113
	v_add_f32_e32 v112, 1.0, v112
	v_add_f32_e32 v113, 1.0, v113
	v_rcp_f32_e32 v112, v112
	v_rcp_f32_e32 v113, v113
	s_nop 0
	v_pk_mul_f32 v[110:111], v[110:111], v[112:113]
	s_nop 0
	v_pk_mul_f32 v[108:109], v[108:109], v[110:111]
	v_mul_f32_e32 v110, 0xbfb8aa3b, v94
	v_mul_f32_e32 v111, 0xbfb8aa3b, v95
	v_exp_f32_e32 v110, v110
	v_exp_f32_e32 v111, v111
	v_add_f32_e32 v110, 1.0, v110
	v_add_f32_e32 v111, 1.0, v111
	v_rcp_f32_e32 v110, v110
	v_rcp_f32_e32 v111, v111
	s_nop 0
	v_pk_mul_f32 v[94:95], v[94:95], v[110:111]
	s_nop 0
	v_pk_mul_f32 v[94:95], v[90:91], v[94:95]
	v_pk_fma_f32 v[90:91], v[96:97], v[178:179], v[84:85] op_sel_hi:[1,0,1]
	s_nop 0
	v_mul_f32_e32 v96, 0xbfb8aa3b, v90
	v_mul_f32_e32 v97, 0xbfb8aa3b, v91
	v_exp_f32_e32 v96, v96
	v_exp_f32_e32 v97, v97
	v_add_f32_e32 v96, 1.0, v96
	v_add_f32_e32 v97, 1.0, v97
	v_rcp_f32_e32 v96, v96
	v_rcp_f32_e32 v97, v97
	s_nop 0
	v_pk_mul_f32 v[90:91], v[90:91], v[96:97]
	s_nop 0
	v_pk_mul_f32 v[96:97], v[92:93], v[90:91]
	v_cvt_pk_bf16_f32 v92, v94, v95
	v_lshrrev_b32_e32 v94, 8, v185
	v_mad_i32_i24 v94, v94, 44, v161
	v_ashrrev_i32_e32 v95, 31, v94
	v_cvt_pk_bf16_f32 v93, v96, v97
	v_lshlrev_b64 v[94:95], 15, v[94:95]
	v_lshlrev_b32_e32 v96, 7, v185
	v_lshl_add_u64 v[94:95], s[14:15], 0, v[94:95]
	v_and_b32_e32 v96, 0x7f80, v96
	v_mov_b32_e32 v97, v0
	v_lshl_add_u64 v[94:95], v[94:95], 0, v[96:97]
	v_cvt_pk_bf16_f32 v90, v106, v107
	v_cvt_pk_bf16_f32 v91, v108, v109
	v_lshl_add_u64 v[94:95], v[94:95], 0, v[130:131]
	global_store_dwordx4 v[94:95], v[90:93], off
	v_pk_fma_f32 v[78:79], v[78:79], v[176:177], v[98:99] op_sel_hi:[1,0,1]
	v_pk_fma_f32 v[74:75], v[74:75], v[176:177], v[102:103] op_sel_hi:[1,0,1]
	v_mul_f32_e32 v90, 0xbfb8aa3b, v78
	v_mul_f32_e32 v91, 0xbfb8aa3b, v79
	v_exp_f32_e32 v90, v90
	v_exp_f32_e32 v91, v91
	v_pk_fma_f32 v[76:77], v[76:77], v[176:177], v[104:105] op_sel_hi:[1,0,1]
	v_pk_fma_f32 v[70:71], v[70:71], v[176:177], v[82:83] op_sel_hi:[1,0,1]
	v_add_f32_e32 v90, 1.0, v90
	v_add_f32_e32 v91, 1.0, v91
	v_rcp_f32_e32 v90, v90
	v_rcp_f32_e32 v91, v91
	v_pk_fma_f32 v[66:67], v[66:67], v[176:177], v[86:87] op_sel_hi:[1,0,1]
	v_pk_fma_f32 v[68:69], v[68:69], v[176:177], v[88:89] op_sel_hi:[1,0,1]
	v_pk_mul_f32 v[78:79], v[78:79], v[90:91]
	s_nop 0
	v_pk_mul_f32 v[74:75], v[74:75], v[78:79]
	v_pk_fma_f32 v[78:79], v[80:81], v[176:177], v[100:101] op_sel_hi:[1,0,1]
	s_nop 0
	v_mul_f32_e32 v80, 0xbfb8aa3b, v78
	v_mul_f32_e32 v81, 0xbfb8aa3b, v79
	v_exp_f32_e32 v80, v80
	v_exp_f32_e32 v81, v81
	v_add_f32_e32 v80, 1.0, v80
	v_add_f32_e32 v81, 1.0, v81
	v_rcp_f32_e32 v80, v80
	v_rcp_f32_e32 v81, v81
	s_nop 0
	v_pk_mul_f32 v[78:79], v[78:79], v[80:81]
	s_nop 0
	v_pk_mul_f32 v[76:77], v[76:77], v[78:79]
	v_mul_f32_e32 v78, 0xbfb8aa3b, v70
	v_mul_f32_e32 v79, 0xbfb8aa3b, v71
	v_exp_f32_e32 v78, v78
	v_exp_f32_e32 v79, v79
	v_add_f32_e32 v78, 1.0, v78
	v_add_f32_e32 v79, 1.0, v79
	v_rcp_f32_e32 v78, v78
	v_rcp_f32_e32 v79, v79
	s_nop 0
	v_pk_mul_f32 v[70:71], v[70:71], v[78:79]
	s_nop 0
	v_pk_mul_f32 v[70:71], v[66:67], v[70:71]
	v_pk_fma_f32 v[66:67], v[72:73], v[176:177], v[84:85] op_sel_hi:[1,0,1]
	s_nop 0
	v_mul_f32_e32 v72, 0xbfb8aa3b, v66
	v_mul_f32_e32 v73, 0xbfb8aa3b, v67
	v_exp_f32_e32 v72, v72
	v_exp_f32_e32 v73, v73
	v_add_f32_e32 v72, 1.0, v72
	v_add_f32_e32 v73, 1.0, v73
	v_rcp_f32_e32 v72, v72
	v_rcp_f32_e32 v73, v73
	s_nop 0
	v_pk_mul_f32 v[66:67], v[66:67], v[72:73]
	s_nop 0
	v_pk_mul_f32 v[72:73], v[68:69], v[66:67]
	v_cvt_pk_bf16_f32 v68, v70, v71
	v_lshrrev_b32_e32 v70, 8, v183
	v_mad_i32_i24 v70, v70, 44, v161
	v_ashrrev_i32_e32 v71, 31, v70
	v_cvt_pk_bf16_f32 v69, v72, v73
	v_lshlrev_b64 v[70:71], 15, v[70:71]
	v_lshlrev_b32_e32 v72, 7, v183
	v_lshl_add_u64 v[70:71], s[14:15], 0, v[70:71]
	v_and_b32_e32 v72, 0x7f80, v72
	v_mov_b32_e32 v73, v0
	v_lshl_add_u64 v[70:71], v[70:71], 0, v[72:73]
	v_cvt_pk_bf16_f32 v66, v74, v75
	v_cvt_pk_bf16_f32 v67, v76, v77
	v_lshl_add_u64 v[70:71], v[70:71], 0, v[130:131]
	global_store_dwordx4 v[70:71], v[66:69], off
	v_pk_fma_f32 v[62:63], v[62:63], v[174:175], v[98:99] op_sel_hi:[1,0,1]
	v_pk_fma_f32 v[58:59], v[58:59], v[174:175], v[102:103] op_sel_hi:[1,0,1]
	v_mul_f32_e32 v66, 0xbfb8aa3b, v62
	v_mul_f32_e32 v67, 0xbfb8aa3b, v63
	v_exp_f32_e32 v66, v66
	v_exp_f32_e32 v67, v67
	v_pk_fma_f32 v[60:61], v[60:61], v[174:175], v[104:105] op_sel_hi:[1,0,1]
	v_pk_fma_f32 v[54:55], v[54:55], v[174:175], v[82:83] op_sel_hi:[1,0,1]
	v_add_f32_e32 v66, 1.0, v66
	v_add_f32_e32 v67, 1.0, v67
	v_rcp_f32_e32 v66, v66
	v_rcp_f32_e32 v67, v67
	v_pk_fma_f32 v[50:51], v[50:51], v[174:175], v[86:87] op_sel_hi:[1,0,1]
	v_pk_fma_f32 v[52:53], v[52:53], v[174:175], v[88:89] op_sel_hi:[1,0,1]
	v_pk_mul_f32 v[62:63], v[62:63], v[66:67]
	s_nop 0
	v_pk_mul_f32 v[58:59], v[58:59], v[62:63]
	v_pk_fma_f32 v[62:63], v[64:65], v[174:175], v[100:101] op_sel_hi:[1,0,1]
	s_nop 0
	v_mul_f32_e32 v64, 0xbfb8aa3b, v62
	v_mul_f32_e32 v65, 0xbfb8aa3b, v63
	v_exp_f32_e32 v64, v64
	v_exp_f32_e32 v65, v65
	v_add_f32_e32 v64, 1.0, v64
	v_add_f32_e32 v65, 1.0, v65
	v_rcp_f32_e32 v64, v64
	v_rcp_f32_e32 v65, v65
	s_nop 0
	v_pk_mul_f32 v[62:63], v[62:63], v[64:65]
	s_nop 0
	v_pk_mul_f32 v[60:61], v[60:61], v[62:63]
	v_mul_f32_e32 v62, 0xbfb8aa3b, v54
	v_mul_f32_e32 v63, 0xbfb8aa3b, v55
	v_exp_f32_e32 v62, v62
	v_exp_f32_e32 v63, v63
	v_add_f32_e32 v62, 1.0, v62
	v_add_f32_e32 v63, 1.0, v63
	v_rcp_f32_e32 v62, v62
	v_rcp_f32_e32 v63, v63
	s_nop 0
	v_pk_mul_f32 v[54:55], v[54:55], v[62:63]
	s_nop 0
	v_pk_mul_f32 v[54:55], v[50:51], v[54:55]
	v_pk_fma_f32 v[50:51], v[56:57], v[174:175], v[84:85] op_sel_hi:[1,0,1]
	s_nop 0
	v_mul_f32_e32 v56, 0xbfb8aa3b, v50
	v_mul_f32_e32 v57, 0xbfb8aa3b, v51
	v_exp_f32_e32 v56, v56
	v_exp_f32_e32 v57, v57
	v_add_f32_e32 v56, 1.0, v56
	v_add_f32_e32 v57, 1.0, v57
	v_rcp_f32_e32 v56, v56
	v_rcp_f32_e32 v57, v57
	s_nop 0
	v_pk_mul_f32 v[50:51], v[50:51], v[56:57]
	s_nop 0
	v_pk_mul_f32 v[56:57], v[52:53], v[50:51]
	v_cvt_pk_bf16_f32 v52, v54, v55
	v_lshrrev_b32_e32 v54, 8, v181
	v_mad_i32_i24 v54, v54, 44, v161
	v_ashrrev_i32_e32 v55, 31, v54
	v_cvt_pk_bf16_f32 v53, v56, v57
	v_lshlrev_b64 v[54:55], 15, v[54:55]
	v_lshlrev_b32_e32 v56, 7, v181
	v_lshl_add_u64 v[54:55], s[14:15], 0, v[54:55]
	v_and_b32_e32 v56, 0x7f80, v56
	v_mov_b32_e32 v57, v0
	v_lshl_add_u64 v[54:55], v[54:55], 0, v[56:57]
	v_cvt_pk_bf16_f32 v50, v58, v59
	v_cvt_pk_bf16_f32 v51, v60, v61
	v_lshl_add_u64 v[54:55], v[54:55], 0, v[130:131]
	global_store_dwordx4 v[54:55], v[50:53], off
	v_pk_fma_f32 v[46:47], v[46:47], v[172:173], v[98:99] op_sel_hi:[1,0,1]
	v_pk_fma_f32 v[42:43], v[42:43], v[172:173], v[102:103] op_sel_hi:[1,0,1]
	v_mul_f32_e32 v50, 0xbfb8aa3b, v46
	v_mul_f32_e32 v51, 0xbfb8aa3b, v47
	v_exp_f32_e32 v50, v50
	v_exp_f32_e32 v51, v51
	v_pk_fma_f32 v[44:45], v[44:45], v[172:173], v[104:105] op_sel_hi:[1,0,1]
	v_pk_fma_f32 v[38:39], v[38:39], v[172:173], v[82:83] op_sel_hi:[1,0,1]
	v_add_f32_e32 v50, 1.0, v50
	v_add_f32_e32 v51, 1.0, v51
	v_rcp_f32_e32 v50, v50
	v_rcp_f32_e32 v51, v51
	v_pk_fma_f32 v[34:35], v[34:35], v[172:173], v[86:87] op_sel_hi:[1,0,1]
	v_pk_fma_f32 v[36:37], v[36:37], v[172:173], v[88:89] op_sel_hi:[1,0,1]
	v_pk_mul_f32 v[46:47], v[46:47], v[50:51]
	s_nop 0
	v_pk_mul_f32 v[42:43], v[42:43], v[46:47]
	v_pk_fma_f32 v[46:47], v[48:49], v[172:173], v[100:101] op_sel_hi:[1,0,1]
	s_nop 0
	v_mul_f32_e32 v48, 0xbfb8aa3b, v46
	v_mul_f32_e32 v49, 0xbfb8aa3b, v47
	v_exp_f32_e32 v48, v48
	v_exp_f32_e32 v49, v49
	v_add_f32_e32 v48, 1.0, v48
	v_add_f32_e32 v49, 1.0, v49
	v_rcp_f32_e32 v48, v48
	v_rcp_f32_e32 v49, v49
	s_nop 0
	v_pk_mul_f32 v[46:47], v[46:47], v[48:49]
	s_nop 0
	v_pk_mul_f32 v[44:45], v[44:45], v[46:47]
	v_mul_f32_e32 v46, 0xbfb8aa3b, v38
	v_mul_f32_e32 v47, 0xbfb8aa3b, v39
	v_exp_f32_e32 v46, v46
	v_exp_f32_e32 v47, v47
	v_add_f32_e32 v46, 1.0, v46
	v_add_f32_e32 v47, 1.0, v47
	v_rcp_f32_e32 v46, v46
	v_rcp_f32_e32 v47, v47
	s_nop 0
	v_pk_mul_f32 v[38:39], v[38:39], v[46:47]
	s_nop 0
	v_pk_mul_f32 v[38:39], v[34:35], v[38:39]
	v_pk_fma_f32 v[34:35], v[40:41], v[172:173], v[84:85] op_sel_hi:[1,0,1]
	s_nop 0
	v_mul_f32_e32 v40, 0xbfb8aa3b, v34
	v_mul_f32_e32 v41, 0xbfb8aa3b, v35
	v_exp_f32_e32 v40, v40
	v_exp_f32_e32 v41, v41
	v_add_f32_e32 v40, 1.0, v40
	v_add_f32_e32 v41, 1.0, v41
	v_rcp_f32_e32 v40, v40
	v_rcp_f32_e32 v41, v41
	s_nop 0
	v_pk_mul_f32 v[34:35], v[34:35], v[40:41]
	s_nop 0
	v_pk_mul_f32 v[40:41], v[36:37], v[34:35]
	v_cvt_pk_bf16_f32 v36, v38, v39
	v_lshrrev_b32_e32 v38, 8, v179
	v_mad_i32_i24 v38, v38, 44, v161
	v_ashrrev_i32_e32 v39, 31, v38
	v_cvt_pk_bf16_f32 v37, v40, v41
	v_lshlrev_b64 v[38:39], 15, v[38:39]
	v_lshlrev_b32_e32 v40, 7, v179
	v_lshl_add_u64 v[38:39], s[14:15], 0, v[38:39]
	v_and_b32_e32 v40, 0x7f80, v40
	v_mov_b32_e32 v41, v0
	v_lshl_add_u64 v[38:39], v[38:39], 0, v[40:41]
	v_cvt_pk_bf16_f32 v34, v42, v43
	v_cvt_pk_bf16_f32 v35, v44, v45
	v_lshl_add_u64 v[38:39], v[38:39], 0, v[130:131]
	global_store_dwordx4 v[38:39], v[34:37], off
	v_pk_fma_f32 v[30:31], v[30:31], v[158:159], v[98:99] op_sel_hi:[1,0,1]
	v_pk_fma_f32 v[26:27], v[26:27], v[158:159], v[102:103] op_sel_hi:[1,0,1]
	v_mul_f32_e32 v34, 0xbfb8aa3b, v30
	v_mul_f32_e32 v35, 0xbfb8aa3b, v31
	v_exp_f32_e32 v34, v34
	v_exp_f32_e32 v35, v35
	v_pk_fma_f32 v[28:29], v[28:29], v[158:159], v[104:105] op_sel_hi:[1,0,1]
	v_pk_fma_f32 v[22:23], v[22:23], v[158:159], v[82:83] op_sel_hi:[1,0,1]
	v_add_f32_e32 v34, 1.0, v34
	v_add_f32_e32 v35, 1.0, v35
	v_rcp_f32_e32 v34, v34
	v_rcp_f32_e32 v35, v35
	v_pk_fma_f32 v[18:19], v[18:19], v[158:159], v[86:87] op_sel_hi:[1,0,1]
	v_pk_fma_f32 v[20:21], v[20:21], v[158:159], v[88:89] op_sel_hi:[1,0,1]
	v_pk_mul_f32 v[30:31], v[30:31], v[34:35]
	s_nop 0
	v_pk_mul_f32 v[26:27], v[26:27], v[30:31]
	v_pk_fma_f32 v[30:31], v[32:33], v[158:159], v[100:101] op_sel_hi:[1,0,1]
	s_nop 0
	v_mul_f32_e32 v32, 0xbfb8aa3b, v30
	v_mul_f32_e32 v33, 0xbfb8aa3b, v31
	v_exp_f32_e32 v32, v32
	v_exp_f32_e32 v33, v33
	v_add_f32_e32 v32, 1.0, v32
	v_add_f32_e32 v33, 1.0, v33
	v_rcp_f32_e32 v32, v32
	v_rcp_f32_e32 v33, v33
	s_nop 0
	v_pk_mul_f32 v[30:31], v[30:31], v[32:33]
	s_nop 0
	v_pk_mul_f32 v[28:29], v[28:29], v[30:31]
	v_mul_f32_e32 v30, 0xbfb8aa3b, v22
	v_mul_f32_e32 v31, 0xbfb8aa3b, v23
	v_exp_f32_e32 v30, v30
	v_exp_f32_e32 v31, v31
	v_add_f32_e32 v30, 1.0, v30
	v_add_f32_e32 v31, 1.0, v31
	v_rcp_f32_e32 v30, v30
	v_rcp_f32_e32 v31, v31
	s_nop 0
	v_pk_mul_f32 v[22:23], v[22:23], v[30:31]
	s_nop 0
	v_pk_mul_f32 v[22:23], v[18:19], v[22:23]
	v_pk_fma_f32 v[18:19], v[24:25], v[158:159], v[84:85] op_sel_hi:[1,0,1]
	s_nop 0
	v_mul_f32_e32 v24, 0xbfb8aa3b, v18
	v_mul_f32_e32 v25, 0xbfb8aa3b, v19
	v_exp_f32_e32 v24, v24
	v_exp_f32_e32 v25, v25
	v_add_f32_e32 v24, 1.0, v24
	v_add_f32_e32 v25, 1.0, v25
	v_rcp_f32_e32 v24, v24
	v_rcp_f32_e32 v25, v25
	s_nop 0
	v_pk_mul_f32 v[18:19], v[18:19], v[24:25]
	s_nop 0
	v_pk_mul_f32 v[24:25], v[20:21], v[18:19]
	v_cvt_pk_bf16_f32 v20, v22, v23
	v_lshrrev_b32_e32 v22, 8, v177
	v_mad_i32_i24 v22, v22, 44, v161
	v_ashrrev_i32_e32 v23, 31, v22
	v_cvt_pk_bf16_f32 v21, v24, v25
	v_lshlrev_b64 v[22:23], 15, v[22:23]
	v_lshlrev_b32_e32 v24, 7, v177
	v_lshl_add_u64 v[22:23], s[14:15], 0, v[22:23]
	v_and_b32_e32 v24, 0x7f80, v24
	v_mov_b32_e32 v25, v0
	v_lshl_add_u64 v[22:23], v[22:23], 0, v[24:25]
	v_cvt_pk_bf16_f32 v18, v26, v27
	v_cvt_pk_bf16_f32 v19, v28, v29
	v_lshl_add_u64 v[22:23], v[22:23], 0, v[130:131]
	global_store_dwordx4 v[22:23], v[18:21], off
	v_pk_fma_f32 v[14:15], v[14:15], v[160:161], v[98:99] op_sel_hi:[1,0,1]
	v_pk_fma_f32 v[10:11], v[10:11], v[160:161], v[102:103] op_sel_hi:[1,0,1]
	v_mul_f32_e32 v18, 0xbfb8aa3b, v14
	v_mul_f32_e32 v19, 0xbfb8aa3b, v15
	v_exp_f32_e32 v18, v18
	v_exp_f32_e32 v19, v19
	v_pk_fma_f32 v[12:13], v[12:13], v[160:161], v[104:105] op_sel_hi:[1,0,1]
	v_pk_fma_f32 v[6:7], v[6:7], v[160:161], v[82:83] op_sel_hi:[1,0,1]
	v_add_f32_e32 v18, 1.0, v18
	v_add_f32_e32 v19, 1.0, v19
	v_rcp_f32_e32 v18, v18
	v_rcp_f32_e32 v19, v19
	v_pk_fma_f32 v[2:3], v[2:3], v[160:161], v[86:87] op_sel_hi:[1,0,1]
	v_pk_fma_f32 v[4:5], v[4:5], v[160:161], v[88:89] op_sel_hi:[1,0,1]
	s_and_b64 vcc, exec, s[36:37]
	v_pk_mul_f32 v[14:15], v[14:15], v[18:19]
	s_mov_b32 s42, s4
	v_pk_mul_f32 v[10:11], v[10:11], v[14:15]
	v_pk_fma_f32 v[14:15], v[16:17], v[160:161], v[100:101] op_sel_hi:[1,0,1]
	s_mov_b32 s12, s6
	v_mul_f32_e32 v16, 0xbfb8aa3b, v14
	v_mul_f32_e32 v17, 0xbfb8aa3b, v15
	v_exp_f32_e32 v16, v16
	v_exp_f32_e32 v17, v17
	s_mov_b64 s[16:17], s[10:11]
	v_add_f32_e32 v16, 1.0, v16
	v_add_f32_e32 v17, 1.0, v17
	v_rcp_f32_e32 v16, v16
	v_rcp_f32_e32 v17, v17
	s_nop 0
	v_pk_mul_f32 v[14:15], v[14:15], v[16:17]
	s_nop 0
	v_pk_mul_f32 v[12:13], v[12:13], v[14:15]
	v_mul_f32_e32 v14, 0xbfb8aa3b, v6
	v_mul_f32_e32 v15, 0xbfb8aa3b, v7
	v_exp_f32_e32 v14, v14
	v_exp_f32_e32 v15, v15
	v_add_f32_e32 v14, 1.0, v14
	v_add_f32_e32 v15, 1.0, v15
	v_rcp_f32_e32 v14, v14
	v_rcp_f32_e32 v15, v15
	s_nop 0
	v_pk_mul_f32 v[6:7], v[6:7], v[14:15]
	s_nop 0
	v_pk_mul_f32 v[6:7], v[2:3], v[6:7]
	v_pk_fma_f32 v[2:3], v[8:9], v[160:161], v[84:85] op_sel_hi:[1,0,1]
	s_nop 0
	v_mul_f32_e32 v8, 0xbfb8aa3b, v2
	v_mul_f32_e32 v9, 0xbfb8aa3b, v3
	v_exp_f32_e32 v8, v8
	v_exp_f32_e32 v9, v9
	v_add_f32_e32 v8, 1.0, v8
	v_add_f32_e32 v9, 1.0, v9
	v_rcp_f32_e32 v8, v8
	v_rcp_f32_e32 v9, v9
	s_nop 0
	v_pk_mul_f32 v[2:3], v[2:3], v[8:9]
	s_nop 0
	v_pk_mul_f32 v[8:9], v[4:5], v[2:3]
	v_cvt_pk_bf16_f32 v4, v6, v7
	v_lshrrev_b32_e32 v6, 8, v175
	v_mad_i32_i24 v6, v6, 44, v161
	v_ashrrev_i32_e32 v7, 31, v6
	v_cvt_pk_bf16_f32 v5, v8, v9
	v_lshlrev_b64 v[6:7], 15, v[6:7]
	v_lshlrev_b32_e32 v8, 7, v175
	v_lshl_add_u64 v[6:7], s[14:15], 0, v[6:7]
	v_and_b32_e32 v8, 0x7f80, v8
	v_mov_b32_e32 v9, v0
	v_lshl_add_u64 v[6:7], v[6:7], 0, v[8:9]
	v_cvt_pk_bf16_f32 v2, v10, v11
	v_cvt_pk_bf16_f32 v3, v12, v13
	v_lshl_add_u64 v[6:7], v[6:7], 0, v[130:131]
	s_mov_b64 s[14:15], s[8:9]
	global_store_dwordx4 v[6:7], v[2:5], off
	s_cbranch_vccnz .LBB0_167

.LBB0_558:
	s_lshl_b32 s5, s12, 8
	v_mov_b32_e32 v82, v171
	v_mov_b32_e32 v83, v1
	s_add_i32 s5, s5, s31
	s_nop 0
	v_add_u32_e32 v182, s5, v82
	s_lshl_b32 s5, s42, 7
	s_or_b32 s5, s5, s34
	v_lshl_add_u32 v186, v83, 3, s5
	s_ashr_i32 s5, s12, 5
	s_mul_hi_i32 s7, s5, 0x5800
	s_mulk_i32 s5, 0x5800
	s_add_u32 s14, s28, s5
	s_addc_u32 s15, s29, s7
	v_ashrrev_i32_e32 v187, 31, v186
	v_lshl_add_u64 v[86:87], v[186:187], 2, s[14:15]
	s_mov_b64 s[14:15], 0x2c00
	s_movk_i32 s5, 0x2000
	global_load_dwordx4 v[82:85], v[86:87], off offset:16
	global_load_dwordx4 v[98:101], v[86:87], off
	v_lshl_add_u64 v[88:89], v[86:87], 0, s[14:15]
	v_add_co_u32_e32 v86, vcc, s5, v86
	v_ashrrev_i32_e32 v183, 31, v182
	s_nop 0
	v_addc_co_u32_e32 v87, vcc, 0, v87, vcc
	v_lshl_add_u64 v[160:161], v[182:183], 2, s[0:1]
	global_load_dwordx4 v[102:105], v[86:87], off offset:3072
	s_nop 0
	global_load_dwordx4 v[86:89], v[88:89], off offset:16
	v_add_u32_e32 v187, 16, v182
	global_load_dword v184, v[160:161], off
	global_load_dword v180, v[160:161], off offset:64
	global_load_dword v178, v[160:161], off offset:128
	global_load_dword v176, v[160:161], off offset:192
	global_load_dword v174, v[160:161], off offset:512
	global_load_dword v172, v[160:161], off offset:576
	global_load_dword v175, v[160:161], off offset:640
	global_load_dword v160, v[160:161], off offset:704
	v_add_u32_e32 v185, 32, v182
	v_add_u32_e32 v183, 48, v182
	v_add_u32_e32 v181, 0x80, v182
	v_add_u32_e32 v179, 0x90, v182
	v_add_u32_e32 v177, 0xa0, v182
	s_waitcnt vmcnt(0)
	v_fmamk_f32 v158, v184, 0x3a800000, v223
	v_cmp_gt_f32_e32 vcc, s95, v158
	v_mul_f32_e32 v168, 0x4b800000, v158
	s_nop 0
	v_cndmask_b32_e32 v158, v158, v168, vcc
	v_rsq_f32_e32 v158, v158
	s_nop 0
	v_mul_f32_e32 v168, 0x45800000, v158
	v_cndmask_b32_e32 v184, v158, v168, vcc
	v_fmamk_f32 v158, v180, 0x3a800000, v223
	v_cmp_gt_f32_e32 vcc, s95, v158
	v_mul_f32_e32 v168, 0x4b800000, v158
	s_nop 0
	v_cndmask_b32_e32 v158, v158, v168, vcc
	v_rsq_f32_e32 v158, v158
	s_nop 0
	v_mul_f32_e32 v168, 0x45800000, v158
	v_cndmask_b32_e32 v180, v158, v168, vcc
	v_fmamk_f32 v158, v178, 0x3a800000, v223
	v_cmp_gt_f32_e32 vcc, s95, v158
	v_mul_f32_e32 v168, 0x4b800000, v158
	s_nop 0
	v_cndmask_b32_e32 v158, v158, v168, vcc
	v_rsq_f32_e32 v158, v158
	s_nop 0
	v_mul_f32_e32 v168, 0x45800000, v158
	v_cndmask_b32_e32 v178, v158, v168, vcc
	v_fmamk_f32 v158, v176, 0x3a800000, v223
	v_cmp_gt_f32_e32 vcc, s95, v158
	v_mul_f32_e32 v168, 0x4b800000, v158
	s_nop 0
	v_cndmask_b32_e32 v158, v158, v168, vcc
	v_rsq_f32_e32 v158, v158
	s_nop 0
	v_mul_f32_e32 v168, 0x45800000, v158
	v_cndmask_b32_e32 v176, v158, v168, vcc
	v_fmamk_f32 v158, v174, 0x3a800000, v223
	v_cmp_gt_f32_e32 vcc, s95, v158
	v_mul_f32_e32 v168, 0x4b800000, v158
	s_nop 0
	v_cndmask_b32_e32 v158, v158, v168, vcc
	v_rsq_f32_e32 v158, v158
	s_nop 0
	v_mul_f32_e32 v168, 0x45800000, v158
	v_cndmask_b32_e32 v174, v158, v168, vcc
	v_fmamk_f32 v158, v172, 0x3a800000, v223
	v_cmp_gt_f32_e32 vcc, s95, v158
	v_mul_f32_e32 v168, 0x4b800000, v158
	s_nop 0
	v_cndmask_b32_e32 v158, v158, v168, vcc
	v_rsq_f32_e32 v158, v158
	s_nop 0
	v_mul_f32_e32 v168, 0x45800000, v158
	v_cndmask_b32_e32 v172, v158, v168, vcc
	v_fmamk_f32 v158, v175, 0x3a800000, v223
	v_add_u32_e32 v175, 0xb0, v182
	v_cmp_gt_f32_e32 vcc, s95, v158
	v_mul_f32_e32 v168, 0x4b800000, v158
	v_fmamk_f32 v160, v160, 0x3a800000, v223
	v_cndmask_b32_e32 v158, v158, v168, vcc
	v_rsq_f32_e32 v158, v158
	v_mul_f32_e32 v161, 0x4b800000, v160
	v_mul_f32_e32 v168, 0x45800000, v158
	v_cndmask_b32_e32 v158, v158, v168, vcc
	v_cmp_gt_f32_e32 vcc, s95, v160
	s_nop 1
	v_cndmask_b32_e32 v160, v160, v161, vcc
	v_rsq_f32_e32 v160, v160
	s_nop 0
	v_mul_f32_e32 v161, 0x45800000, v160
	v_cndmask_b32_e32 v160, v160, v161, vcc
	v_ashrrev_i32_e32 v161, 6, v186
	v_and_b32_e32 v186, 56, v186
	v_pk_fma_f32 v[138:139], v[138:139], v[184:185], v[98:99] op_sel_hi:[1,0,1]
	v_pk_fma_f32 v[142:143], v[142:143], v[184:185], v[102:103] op_sel_hi:[1,0,1]
	v_mul_f32_e32 v168, 0xbfb8aa3b, v138
	v_mul_f32_e32 v169, 0xbfb8aa3b, v139
	v_exp_f32_e32 v168, v168
	v_exp_f32_e32 v169, v169
	v_pk_fma_f32 v[140:141], v[140:141], v[184:185], v[100:101] op_sel_hi:[1,0,1]
	v_pk_fma_f32 v[134:135], v[134:135], v[184:185], v[82:83] op_sel_hi:[1,0,1]
	v_add_f32_e32 v168, 1.0, v168
	v_add_f32_e32 v169, 1.0, v169
	v_rcp_f32_e32 v168, v168
	v_rcp_f32_e32 v169, v169
	v_pk_fma_f32 v[130:131], v[130:131], v[184:185], v[86:87] op_sel_hi:[1,0,1]
	v_pk_fma_f32 v[132:133], v[132:133], v[184:185], v[88:89] op_sel_hi:[1,0,1]
	v_readlane_b32 s14, v254, 27
	v_pk_mul_f32 v[138:139], v[138:139], v[168:169]
	v_readlane_b32 s15, v254, 28
	v_pk_mul_f32 v[138:139], v[142:143], v[138:139]
	v_pk_fma_f32 v[142:143], v[144:145], v[184:185], v[104:105] op_sel_hi:[1,0,1]
	v_mul_f32_e32 v144, 0xbfb8aa3b, v140
	v_mul_f32_e32 v145, 0xbfb8aa3b, v141
	v_exp_f32_e32 v144, v144
	v_exp_f32_e32 v145, v145
	v_add_f32_e32 v144, 1.0, v144
	v_add_f32_e32 v145, 1.0, v145
	v_rcp_f32_e32 v144, v144
	v_rcp_f32_e32 v145, v145
	s_nop 0
	v_pk_mul_f32 v[140:141], v[140:141], v[144:145]
	s_nop 0
	v_pk_mul_f32 v[140:141], v[142:143], v[140:141]
	v_mul_f32_e32 v142, 0xbfb8aa3b, v134
	v_mul_f32_e32 v143, 0xbfb8aa3b, v135
	v_exp_f32_e32 v142, v142
	v_exp_f32_e32 v143, v143
	v_add_f32_e32 v142, 1.0, v142
	v_add_f32_e32 v143, 1.0, v143
	v_rcp_f32_e32 v142, v142
	v_rcp_f32_e32 v143, v143
	s_nop 0
	v_pk_mul_f32 v[134:135], v[134:135], v[142:143]
	s_nop 0
	v_pk_mul_f32 v[130:131], v[130:131], v[134:135]
	v_pk_fma_f32 v[134:135], v[136:137], v[184:185], v[84:85] op_sel_hi:[1,0,1]
	s_nop 0
	v_mul_f32_e32 v136, 0xbfb8aa3b, v134
	v_mul_f32_e32 v137, 0xbfb8aa3b, v135
	v_exp_f32_e32 v136, v136
	v_exp_f32_e32 v137, v137
	v_add_f32_e32 v136, 1.0, v136
	v_add_f32_e32 v137, 1.0, v137
	v_rcp_f32_e32 v136, v136
	v_rcp_f32_e32 v137, v137
	s_nop 0
	v_pk_mul_f32 v[134:135], v[134:135], v[136:137]
	s_nop 0
	v_pk_mul_f32 v[136:137], v[132:133], v[134:135]
	v_cvt_pk_bf16_f32 v134, v130, v131
	v_lshrrev_b32_e32 v130, 8, v182
	v_mad_i32_i24 v130, v130, 44, v161
	v_ashrrev_i32_e32 v131, 31, v130
	v_cvt_pk_bf16_f32 v135, v136, v137
	v_lshlrev_b64 v[130:131], 15, v[130:131]
	v_lshlrev_b32_e32 v136, 7, v182
	v_lshl_add_u64 v[130:131], s[14:15], 0, v[130:131]
	v_and_b32_e32 v136, 0x7f80, v136
	v_mov_b32_e32 v137, v0
	v_lshl_add_u64 v[136:137], v[130:131], 0, v[136:137]
	v_lshlrev_b32_e32 v130, 1, v186
	v_mov_b32_e32 v131, v0
	v_cvt_pk_bf16_f32 v132, v138, v139
	v_cvt_pk_bf16_f32 v133, v140, v141
	v_lshl_add_u64 v[136:137], v[136:137], 0, v[130:131]
	global_store_dwordx4 v[136:137], v[132:135], off
	v_pk_fma_f32 v[126:127], v[126:127], v[180:181], v[98:99] op_sel_hi:[1,0,1]
	v_pk_fma_f32 v[122:123], v[122:123], v[180:181], v[102:103] op_sel_hi:[1,0,1]
	v_mul_f32_e32 v132, 0xbfb8aa3b, v126
	v_mul_f32_e32 v133, 0xbfb8aa3b, v127
	v_exp_f32_e32 v132, v132
	v_exp_f32_e32 v133, v133
	v_pk_fma_f32 v[124:125], v[124:125], v[180:181], v[104:105] op_sel_hi:[1,0,1]
	v_pk_fma_f32 v[118:119], v[118:119], v[180:181], v[82:83] op_sel_hi:[1,0,1]
	v_add_f32_e32 v132, 1.0, v132
	v_add_f32_e32 v133, 1.0, v133
	v_rcp_f32_e32 v132, v132
	v_rcp_f32_e32 v133, v133
	v_pk_fma_f32 v[114:115], v[114:115], v[180:181], v[86:87] op_sel_hi:[1,0,1]
	v_pk_fma_f32 v[116:117], v[116:117], v[180:181], v[88:89] op_sel_hi:[1,0,1]
	v_pk_mul_f32 v[126:127], v[126:127], v[132:133]
	s_nop 0
	v_pk_mul_f32 v[122:123], v[122:123], v[126:127]
	v_pk_fma_f32 v[126:127], v[128:129], v[180:181], v[100:101] op_sel_hi:[1,0,1]
	s_nop 0
	v_mul_f32_e32 v128, 0xbfb8aa3b, v126
	v_mul_f32_e32 v129, 0xbfb8aa3b, v127
	v_exp_f32_e32 v128, v128
	v_exp_f32_e32 v129, v129
	v_add_f32_e32 v128, 1.0, v128
	v_add_f32_e32 v129, 1.0, v129
	v_rcp_f32_e32 v128, v128
	v_rcp_f32_e32 v129, v129
	s_nop 0
	v_pk_mul_f32 v[126:127], v[126:127], v[128:129]
	s_nop 0
	v_pk_mul_f32 v[124:125], v[124:125], v[126:127]
	v_mul_f32_e32 v126, 0xbfb8aa3b, v118
	v_mul_f32_e32 v127, 0xbfb8aa3b, v119
	v_exp_f32_e32 v126, v126
	v_exp_f32_e32 v127, v127
	v_add_f32_e32 v126, 1.0, v126
	v_add_f32_e32 v127, 1.0, v127
	v_rcp_f32_e32 v126, v126
	v_rcp_f32_e32 v127, v127
	s_nop 0
	v_pk_mul_f32 v[118:119], v[118:119], v[126:127]
	s_nop 0
	v_pk_mul_f32 v[118:119], v[114:115], v[118:119]
	v_pk_fma_f32 v[114:115], v[120:121], v[180:181], v[84:85] op_sel_hi:[1,0,1]
	s_nop 0
	v_mul_f32_e32 v120, 0xbfb8aa3b, v114
	v_mul_f32_e32 v121, 0xbfb8aa3b, v115
	v_exp_f32_e32 v120, v120
	v_exp_f32_e32 v121, v121
	v_add_f32_e32 v120, 1.0, v120
	v_add_f32_e32 v121, 1.0, v121
	v_rcp_f32_e32 v120, v120
	v_rcp_f32_e32 v121, v121
	s_nop 0
	v_pk_mul_f32 v[114:115], v[114:115], v[120:121]
	s_nop 0
	v_pk_mul_f32 v[120:121], v[116:117], v[114:115]
	v_cvt_pk_bf16_f32 v116, v118, v119
	v_lshrrev_b32_e32 v118, 8, v187
	v_mad_i32_i24 v118, v118, 44, v161
	v_ashrrev_i32_e32 v119, 31, v118
	v_cvt_pk_bf16_f32 v117, v120, v121
	v_lshlrev_b64 v[118:119], 15, v[118:119]
	v_lshlrev_b32_e32 v120, 7, v187
	v_lshl_add_u64 v[118:119], s[14:15], 0, v[118:119]
	v_and_b32_e32 v120, 0x7f80, v120
	v_mov_b32_e32 v121, v0
	v_lshl_add_u64 v[118:119], v[118:119], 0, v[120:121]
	v_cvt_pk_bf16_f32 v114, v122, v123
	v_cvt_pk_bf16_f32 v115, v124, v125
	v_lshl_add_u64 v[118:119], v[118:119], 0, v[130:131]
	global_store_dwordx4 v[118:119], v[114:117], off
	v_pk_fma_f32 v[110:111], v[110:111], v[178:179], v[98:99] op_sel_hi:[1,0,1]
	v_pk_fma_f32 v[106:107], v[106:107], v[178:179], v[102:103] op_sel_hi:[1,0,1]
	v_mul_f32_e32 v114, 0xbfb8aa3b, v110
	v_mul_f32_e32 v115, 0xbfb8aa3b, v111
	v_exp_f32_e32 v114, v114
	v_exp_f32_e32 v115, v115
	v_pk_fma_f32 v[108:109], v[108:109], v[178:179], v[104:105] op_sel_hi:[1,0,1]
	v_pk_fma_f32 v[94:95], v[94:95], v[178:179], v[82:83] op_sel_hi:[1,0,1]
	v_add_f32_e32 v114, 1.0, v114
	v_add_f32_e32 v115, 1.0, v115
	v_rcp_f32_e32 v114, v114
	v_rcp_f32_e32 v115, v115
	v_pk_fma_f32 v[90:91], v[90:91], v[178:179], v[86:87] op_sel_hi:[1,0,1]
	v_pk_fma_f32 v[92:93], v[92:93], v[178:179], v[88:89] op_sel_hi:[1,0,1]
	v_pk_mul_f32 v[110:111], v[110:111], v[114:115]
	s_nop 0
	v_pk_mul_f32 v[106:107], v[106:107], v[110:111]
	v_pk_fma_f32 v[110:111], v[112:113], v[178:179], v[100:101] op_sel_hi:[1,0,1]
	s_nop 0
	v_mul_f32_e32 v112, 0xbfb8aa3b, v110
	v_mul_f32_e32 v113, 0xbfb8aa3b, v111
	v_exp_f32_e32 v112, v112
	v_exp_f32_e32 v113, v113
	v_add_f32_e32 v112, 1.0, v112
	v_add_f32_e32 v113, 1.0, v113
	v_rcp_f32_e32 v112, v112
	v_rcp_f32_e32 v113, v113
	s_nop 0
	v_pk_mul_f32 v[110:111], v[110:111], v[112:113]
	s_nop 0
	v_pk_mul_f32 v[108:109], v[108:109], v[110:111]
	v_mul_f32_e32 v110, 0xbfb8aa3b, v94
	v_mul_f32_e32 v111, 0xbfb8aa3b, v95
	v_exp_f32_e32 v110, v110
	v_exp_f32_e32 v111, v111
	v_add_f32_e32 v110, 1.0, v110
	v_add_f32_e32 v111, 1.0, v111
	v_rcp_f32_e32 v110, v110
	v_rcp_f32_e32 v111, v111
	s_nop 0
	v_pk_mul_f32 v[94:95], v[94:95], v[110:111]
	s_nop 0
	v_pk_mul_f32 v[94:95], v[90:91], v[94:95]
	v_pk_fma_f32 v[90:91], v[96:97], v[178:179], v[84:85] op_sel_hi:[1,0,1]
	s_nop 0
	v_mul_f32_e32 v96, 0xbfb8aa3b, v90
	v_mul_f32_e32 v97, 0xbfb8aa3b, v91
	v_exp_f32_e32 v96, v96
	v_exp_f32_e32 v97, v97
	v_add_f32_e32 v96, 1.0, v96
	v_add_f32_e32 v97, 1.0, v97
	v_rcp_f32_e32 v96, v96
	v_rcp_f32_e32 v97, v97
	s_nop 0
	v_pk_mul_f32 v[90:91], v[90:91], v[96:97]
	s_nop 0
	v_pk_mul_f32 v[96:97], v[92:93], v[90:91]
	v_cvt_pk_bf16_f32 v92, v94, v95
	v_lshrrev_b32_e32 v94, 8, v185
	v_mad_i32_i24 v94, v94, 44, v161
	v_ashrrev_i32_e32 v95, 31, v94
	v_cvt_pk_bf16_f32 v93, v96, v97
	v_lshlrev_b64 v[94:95], 15, v[94:95]
	v_lshlrev_b32_e32 v96, 7, v185
	v_lshl_add_u64 v[94:95], s[14:15], 0, v[94:95]
	v_and_b32_e32 v96, 0x7f80, v96
	v_mov_b32_e32 v97, v0
	v_lshl_add_u64 v[94:95], v[94:95], 0, v[96:97]
	v_cvt_pk_bf16_f32 v90, v106, v107
	v_cvt_pk_bf16_f32 v91, v108, v109
	v_lshl_add_u64 v[94:95], v[94:95], 0, v[130:131]
	global_store_dwordx4 v[94:95], v[90:93], off
	v_pk_fma_f32 v[78:79], v[78:79], v[176:177], v[98:99] op_sel_hi:[1,0,1]
	v_pk_fma_f32 v[74:75], v[74:75], v[176:177], v[102:103] op_sel_hi:[1,0,1]
	v_mul_f32_e32 v90, 0xbfb8aa3b, v78
	v_mul_f32_e32 v91, 0xbfb8aa3b, v79
	v_exp_f32_e32 v90, v90
	v_exp_f32_e32 v91, v91
	v_pk_fma_f32 v[76:77], v[76:77], v[176:177], v[104:105] op_sel_hi:[1,0,1]
	v_pk_fma_f32 v[70:71], v[70:71], v[176:177], v[82:83] op_sel_hi:[1,0,1]
	v_add_f32_e32 v90, 1.0, v90
	v_add_f32_e32 v91, 1.0, v91
	v_rcp_f32_e32 v90, v90
	v_rcp_f32_e32 v91, v91
	v_pk_fma_f32 v[66:67], v[66:67], v[176:177], v[86:87] op_sel_hi:[1,0,1]
	v_pk_fma_f32 v[68:69], v[68:69], v[176:177], v[88:89] op_sel_hi:[1,0,1]
	v_pk_mul_f32 v[78:79], v[78:79], v[90:91]
	s_nop 0
	v_pk_mul_f32 v[74:75], v[74:75], v[78:79]
	v_pk_fma_f32 v[78:79], v[80:81], v[176:177], v[100:101] op_sel_hi:[1,0,1]
	s_nop 0
	v_mul_f32_e32 v80, 0xbfb8aa3b, v78
	v_mul_f32_e32 v81, 0xbfb8aa3b, v79
	v_exp_f32_e32 v80, v80
	v_exp_f32_e32 v81, v81
	v_add_f32_e32 v80, 1.0, v80
	v_add_f32_e32 v81, 1.0, v81
	v_rcp_f32_e32 v80, v80
	v_rcp_f32_e32 v81, v81
	s_nop 0
	v_pk_mul_f32 v[78:79], v[78:79], v[80:81]
	s_nop 0
	v_pk_mul_f32 v[76:77], v[76:77], v[78:79]
	v_mul_f32_e32 v78, 0xbfb8aa3b, v70
	v_mul_f32_e32 v79, 0xbfb8aa3b, v71
	v_exp_f32_e32 v78, v78
	v_exp_f32_e32 v79, v79
	v_add_f32_e32 v78, 1.0, v78
	v_add_f32_e32 v79, 1.0, v79
	v_rcp_f32_e32 v78, v78
	v_rcp_f32_e32 v79, v79
	s_nop 0
	v_pk_mul_f32 v[70:71], v[70:71], v[78:79]
	s_nop 0
	v_pk_mul_f32 v[70:71], v[66:67], v[70:71]
	v_pk_fma_f32 v[66:67], v[72:73], v[176:177], v[84:85] op_sel_hi:[1,0,1]
	s_nop 0
	v_mul_f32_e32 v72, 0xbfb8aa3b, v66
	v_mul_f32_e32 v73, 0xbfb8aa3b, v67
	v_exp_f32_e32 v72, v72
	v_exp_f32_e32 v73, v73
	v_add_f32_e32 v72, 1.0, v72
	v_add_f32_e32 v73, 1.0, v73
	v_rcp_f32_e32 v72, v72
	v_rcp_f32_e32 v73, v73
	s_nop 0
	v_pk_mul_f32 v[66:67], v[66:67], v[72:73]
	s_nop 0
	v_pk_mul_f32 v[72:73], v[68:69], v[66:67]
	v_cvt_pk_bf16_f32 v68, v70, v71
	v_lshrrev_b32_e32 v70, 8, v183
	v_mad_i32_i24 v70, v70, 44, v161
	v_ashrrev_i32_e32 v71, 31, v70
	v_cvt_pk_bf16_f32 v69, v72, v73
	v_lshlrev_b64 v[70:71], 15, v[70:71]
	v_lshlrev_b32_e32 v72, 7, v183
	v_lshl_add_u64 v[70:71], s[14:15], 0, v[70:71]
	v_and_b32_e32 v72, 0x7f80, v72
	v_mov_b32_e32 v73, v0
	v_lshl_add_u64 v[70:71], v[70:71], 0, v[72:73]
	v_cvt_pk_bf16_f32 v66, v74, v75
	v_cvt_pk_bf16_f32 v67, v76, v77
	v_lshl_add_u64 v[70:71], v[70:71], 0, v[130:131]
	global_store_dwordx4 v[70:71], v[66:69], off
	v_pk_fma_f32 v[62:63], v[62:63], v[174:175], v[98:99] op_sel_hi:[1,0,1]
	v_pk_fma_f32 v[58:59], v[58:59], v[174:175], v[102:103] op_sel_hi:[1,0,1]
	v_mul_f32_e32 v66, 0xbfb8aa3b, v62
	v_mul_f32_e32 v67, 0xbfb8aa3b, v63
	v_exp_f32_e32 v66, v66
	v_exp_f32_e32 v67, v67
	v_pk_fma_f32 v[60:61], v[60:61], v[174:175], v[104:105] op_sel_hi:[1,0,1]
	v_pk_fma_f32 v[54:55], v[54:55], v[174:175], v[82:83] op_sel_hi:[1,0,1]
	v_add_f32_e32 v66, 1.0, v66
	v_add_f32_e32 v67, 1.0, v67
	v_rcp_f32_e32 v66, v66
	v_rcp_f32_e32 v67, v67
	v_pk_fma_f32 v[50:51], v[50:51], v[174:175], v[86:87] op_sel_hi:[1,0,1]
	v_pk_fma_f32 v[52:53], v[52:53], v[174:175], v[88:89] op_sel_hi:[1,0,1]
	v_pk_mul_f32 v[62:63], v[62:63], v[66:67]
	s_nop 0
	v_pk_mul_f32 v[58:59], v[58:59], v[62:63]
	v_pk_fma_f32 v[62:63], v[64:65], v[174:175], v[100:101] op_sel_hi:[1,0,1]
	s_nop 0
	v_mul_f32_e32 v64, 0xbfb8aa3b, v62
	v_mul_f32_e32 v65, 0xbfb8aa3b, v63
	v_exp_f32_e32 v64, v64
	v_exp_f32_e32 v65, v65
	v_add_f32_e32 v64, 1.0, v64
	v_add_f32_e32 v65, 1.0, v65
	v_rcp_f32_e32 v64, v64
	v_rcp_f32_e32 v65, v65
	s_nop 0
	v_pk_mul_f32 v[62:63], v[62:63], v[64:65]
	s_nop 0
	v_pk_mul_f32 v[60:61], v[60:61], v[62:63]
	v_mul_f32_e32 v62, 0xbfb8aa3b, v54
	v_mul_f32_e32 v63, 0xbfb8aa3b, v55
	v_exp_f32_e32 v62, v62
	v_exp_f32_e32 v63, v63
	v_add_f32_e32 v62, 1.0, v62
	v_add_f32_e32 v63, 1.0, v63
	v_rcp_f32_e32 v62, v62
	v_rcp_f32_e32 v63, v63
	s_nop 0
	v_pk_mul_f32 v[54:55], v[54:55], v[62:63]
	s_nop 0
	v_pk_mul_f32 v[54:55], v[50:51], v[54:55]
	v_pk_fma_f32 v[50:51], v[56:57], v[174:175], v[84:85] op_sel_hi:[1,0,1]
	s_nop 0
	v_mul_f32_e32 v56, 0xbfb8aa3b, v50
	v_mul_f32_e32 v57, 0xbfb8aa3b, v51
	v_exp_f32_e32 v56, v56
	v_exp_f32_e32 v57, v57
	v_add_f32_e32 v56, 1.0, v56
	v_add_f32_e32 v57, 1.0, v57
	v_rcp_f32_e32 v56, v56
	v_rcp_f32_e32 v57, v57
	s_nop 0
	v_pk_mul_f32 v[50:51], v[50:51], v[56:57]
	s_nop 0
	v_pk_mul_f32 v[56:57], v[52:53], v[50:51]
	v_cvt_pk_bf16_f32 v52, v54, v55
	v_lshrrev_b32_e32 v54, 8, v181
	v_mad_i32_i24 v54, v54, 44, v161
	v_ashrrev_i32_e32 v55, 31, v54
	v_cvt_pk_bf16_f32 v53, v56, v57
	v_lshlrev_b64 v[54:55], 15, v[54:55]
	v_lshlrev_b32_e32 v56, 7, v181
	v_lshl_add_u64 v[54:55], s[14:15], 0, v[54:55]
	v_and_b32_e32 v56, 0x7f80, v56
	v_mov_b32_e32 v57, v0
	v_lshl_add_u64 v[54:55], v[54:55], 0, v[56:57]
	v_cvt_pk_bf16_f32 v50, v58, v59
	v_cvt_pk_bf16_f32 v51, v60, v61
	v_lshl_add_u64 v[54:55], v[54:55], 0, v[130:131]
	global_store_dwordx4 v[54:55], v[50:53], off
	v_pk_fma_f32 v[46:47], v[46:47], v[172:173], v[98:99] op_sel_hi:[1,0,1]
	v_pk_fma_f32 v[42:43], v[42:43], v[172:173], v[102:103] op_sel_hi:[1,0,1]
	v_mul_f32_e32 v50, 0xbfb8aa3b, v46
	v_mul_f32_e32 v51, 0xbfb8aa3b, v47
	v_exp_f32_e32 v50, v50
	v_exp_f32_e32 v51, v51
	v_pk_fma_f32 v[44:45], v[44:45], v[172:173], v[104:105] op_sel_hi:[1,0,1]
	v_pk_fma_f32 v[38:39], v[38:39], v[172:173], v[82:83] op_sel_hi:[1,0,1]
	v_add_f32_e32 v50, 1.0, v50
	v_add_f32_e32 v51, 1.0, v51
	v_rcp_f32_e32 v50, v50
	v_rcp_f32_e32 v51, v51
	v_pk_fma_f32 v[34:35], v[34:35], v[172:173], v[86:87] op_sel_hi:[1,0,1]
	v_pk_fma_f32 v[36:37], v[36:37], v[172:173], v[88:89] op_sel_hi:[1,0,1]
	v_pk_mul_f32 v[46:47], v[46:47], v[50:51]
	s_nop 0
	v_pk_mul_f32 v[42:43], v[42:43], v[46:47]
	v_pk_fma_f32 v[46:47], v[48:49], v[172:173], v[100:101] op_sel_hi:[1,0,1]
	s_nop 0
	v_mul_f32_e32 v48, 0xbfb8aa3b, v46
	v_mul_f32_e32 v49, 0xbfb8aa3b, v47
	v_exp_f32_e32 v48, v48
	v_exp_f32_e32 v49, v49
	v_add_f32_e32 v48, 1.0, v48
	v_add_f32_e32 v49, 1.0, v49
	v_rcp_f32_e32 v48, v48
	v_rcp_f32_e32 v49, v49
	s_nop 0
	v_pk_mul_f32 v[46:47], v[46:47], v[48:49]
	s_nop 0
	v_pk_mul_f32 v[44:45], v[44:45], v[46:47]
	v_mul_f32_e32 v46, 0xbfb8aa3b, v38
	v_mul_f32_e32 v47, 0xbfb8aa3b, v39
	v_exp_f32_e32 v46, v46
	v_exp_f32_e32 v47, v47
	v_add_f32_e32 v46, 1.0, v46
	v_add_f32_e32 v47, 1.0, v47
	v_rcp_f32_e32 v46, v46
	v_rcp_f32_e32 v47, v47
	s_nop 0
	v_pk_mul_f32 v[38:39], v[38:39], v[46:47]
	s_nop 0
	v_pk_mul_f32 v[38:39], v[34:35], v[38:39]
	v_pk_fma_f32 v[34:35], v[40:41], v[172:173], v[84:85] op_sel_hi:[1,0,1]
	s_nop 0
	v_mul_f32_e32 v40, 0xbfb8aa3b, v34
	v_mul_f32_e32 v41, 0xbfb8aa3b, v35
	v_exp_f32_e32 v40, v40
	v_exp_f32_e32 v41, v41
	v_add_f32_e32 v40, 1.0, v40
	v_add_f32_e32 v41, 1.0, v41
	v_rcp_f32_e32 v40, v40
	v_rcp_f32_e32 v41, v41
	s_nop 0
	v_pk_mul_f32 v[34:35], v[34:35], v[40:41]
	s_nop 0
	v_pk_mul_f32 v[40:41], v[36:37], v[34:35]
	v_cvt_pk_bf16_f32 v36, v38, v39
	v_lshrrev_b32_e32 v38, 8, v179
	v_mad_i32_i24 v38, v38, 44, v161
	v_ashrrev_i32_e32 v39, 31, v38
	v_cvt_pk_bf16_f32 v37, v40, v41
	v_lshlrev_b64 v[38:39], 15, v[38:39]
	v_lshlrev_b32_e32 v40, 7, v179
	v_lshl_add_u64 v[38:39], s[14:15], 0, v[38:39]
	v_and_b32_e32 v40, 0x7f80, v40
	v_mov_b32_e32 v41, v0
	v_lshl_add_u64 v[38:39], v[38:39], 0, v[40:41]
	v_cvt_pk_bf16_f32 v34, v42, v43
	v_cvt_pk_bf16_f32 v35, v44, v45
	v_lshl_add_u64 v[38:39], v[38:39], 0, v[130:131]
	global_store_dwordx4 v[38:39], v[34:37], off
	v_pk_fma_f32 v[30:31], v[30:31], v[158:159], v[98:99] op_sel_hi:[1,0,1]
	v_pk_fma_f32 v[26:27], v[26:27], v[158:159], v[102:103] op_sel_hi:[1,0,1]
	v_mul_f32_e32 v34, 0xbfb8aa3b, v30
	v_mul_f32_e32 v35, 0xbfb8aa3b, v31
	v_exp_f32_e32 v34, v34
	v_exp_f32_e32 v35, v35
	v_pk_fma_f32 v[28:29], v[28:29], v[158:159], v[104:105] op_sel_hi:[1,0,1]
	v_pk_fma_f32 v[22:23], v[22:23], v[158:159], v[82:83] op_sel_hi:[1,0,1]
	v_add_f32_e32 v34, 1.0, v34
	v_add_f32_e32 v35, 1.0, v35
	v_rcp_f32_e32 v34, v34
	v_rcp_f32_e32 v35, v35
	v_pk_fma_f32 v[18:19], v[18:19], v[158:159], v[86:87] op_sel_hi:[1,0,1]
	v_pk_fma_f32 v[20:21], v[20:21], v[158:159], v[88:89] op_sel_hi:[1,0,1]
	v_pk_mul_f32 v[30:31], v[30:31], v[34:35]
	s_nop 0
	v_pk_mul_f32 v[26:27], v[26:27], v[30:31]
	v_pk_fma_f32 v[30:31], v[32:33], v[158:159], v[100:101] op_sel_hi:[1,0,1]
	s_nop 0
	v_mul_f32_e32 v32, 0xbfb8aa3b, v30
	v_mul_f32_e32 v33, 0xbfb8aa3b, v31
	v_exp_f32_e32 v32, v32
	v_exp_f32_e32 v33, v33
	v_add_f32_e32 v32, 1.0, v32
	v_add_f32_e32 v33, 1.0, v33
	v_rcp_f32_e32 v32, v32
	v_rcp_f32_e32 v33, v33
	s_nop 0
	v_pk_mul_f32 v[30:31], v[30:31], v[32:33]
	s_nop 0
	v_pk_mul_f32 v[28:29], v[28:29], v[30:31]
	v_mul_f32_e32 v30, 0xbfb8aa3b, v22
	v_mul_f32_e32 v31, 0xbfb8aa3b, v23
	v_exp_f32_e32 v30, v30
	v_exp_f32_e32 v31, v31
	v_add_f32_e32 v30, 1.0, v30
	v_add_f32_e32 v31, 1.0, v31
	v_rcp_f32_e32 v30, v30
	v_rcp_f32_e32 v31, v31
	s_nop 0
	v_pk_mul_f32 v[22:23], v[22:23], v[30:31]
	s_nop 0
	v_pk_mul_f32 v[22:23], v[18:19], v[22:23]
	v_pk_fma_f32 v[18:19], v[24:25], v[158:159], v[84:85] op_sel_hi:[1,0,1]
	s_nop 0
	v_mul_f32_e32 v24, 0xbfb8aa3b, v18
	v_mul_f32_e32 v25, 0xbfb8aa3b, v19
	v_exp_f32_e32 v24, v24
	v_exp_f32_e32 v25, v25
	v_add_f32_e32 v24, 1.0, v24
	v_add_f32_e32 v25, 1.0, v25
	v_rcp_f32_e32 v24, v24
	v_rcp_f32_e32 v25, v25
	s_nop 0
	v_pk_mul_f32 v[18:19], v[18:19], v[24:25]
	s_nop 0
	v_pk_mul_f32 v[24:25], v[20:21], v[18:19]
	v_cvt_pk_bf16_f32 v20, v22, v23
	v_lshrrev_b32_e32 v22, 8, v177
	v_mad_i32_i24 v22, v22, 44, v161
	v_ashrrev_i32_e32 v23, 31, v22
	v_cvt_pk_bf16_f32 v21, v24, v25
	v_lshlrev_b64 v[22:23], 15, v[22:23]
	v_lshlrev_b32_e32 v24, 7, v177
	v_lshl_add_u64 v[22:23], s[14:15], 0, v[22:23]
	v_and_b32_e32 v24, 0x7f80, v24
	v_mov_b32_e32 v25, v0
	v_lshl_add_u64 v[22:23], v[22:23], 0, v[24:25]
	v_cvt_pk_bf16_f32 v18, v26, v27
	v_cvt_pk_bf16_f32 v19, v28, v29
	v_lshl_add_u64 v[22:23], v[22:23], 0, v[130:131]
	global_store_dwordx4 v[22:23], v[18:21], off
	v_pk_fma_f32 v[14:15], v[14:15], v[160:161], v[98:99] op_sel_hi:[1,0,1]
	v_pk_fma_f32 v[10:11], v[10:11], v[160:161], v[102:103] op_sel_hi:[1,0,1]
	v_mul_f32_e32 v18, 0xbfb8aa3b, v14
	v_mul_f32_e32 v19, 0xbfb8aa3b, v15
	v_exp_f32_e32 v18, v18
	v_exp_f32_e32 v19, v19
	v_pk_fma_f32 v[12:13], v[12:13], v[160:161], v[104:105] op_sel_hi:[1,0,1]
	v_pk_fma_f32 v[6:7], v[6:7], v[160:161], v[82:83] op_sel_hi:[1,0,1]
	v_add_f32_e32 v18, 1.0, v18
	v_add_f32_e32 v19, 1.0, v19
	v_rcp_f32_e32 v18, v18
	v_rcp_f32_e32 v19, v19
	v_pk_fma_f32 v[2:3], v[2:3], v[160:161], v[86:87] op_sel_hi:[1,0,1]
	v_pk_fma_f32 v[4:5], v[4:5], v[160:161], v[88:89] op_sel_hi:[1,0,1]
	s_and_b64 vcc, exec, s[36:37]
	v_pk_mul_f32 v[14:15], v[14:15], v[18:19]
	s_mov_b32 s42, s4
	v_pk_mul_f32 v[10:11], v[10:11], v[14:15]
	v_pk_fma_f32 v[14:15], v[16:17], v[160:161], v[100:101] op_sel_hi:[1,0,1]
	s_mov_b32 s12, s6
	v_mul_f32_e32 v16, 0xbfb8aa3b, v14
	v_mul_f32_e32 v17, 0xbfb8aa3b, v15
	v_exp_f32_e32 v16, v16
	v_exp_f32_e32 v17, v17
	s_mov_b64 s[16:17], s[10:11]
	v_add_f32_e32 v16, 1.0, v16
	v_add_f32_e32 v17, 1.0, v17
	v_rcp_f32_e32 v16, v16
	v_rcp_f32_e32 v17, v17
	s_nop 0
	v_pk_mul_f32 v[14:15], v[14:15], v[16:17]
	s_nop 0
	v_pk_mul_f32 v[12:13], v[12:13], v[14:15]
	v_mul_f32_e32 v14, 0xbfb8aa3b, v6
	v_mul_f32_e32 v15, 0xbfb8aa3b, v7
	v_exp_f32_e32 v14, v14
	v_exp_f32_e32 v15, v15
	v_add_f32_e32 v14, 1.0, v14
	v_add_f32_e32 v15, 1.0, v15
	v_rcp_f32_e32 v14, v14
	v_rcp_f32_e32 v15, v15
	s_nop 0
	v_pk_mul_f32 v[6:7], v[6:7], v[14:15]
	s_nop 0
	v_pk_mul_f32 v[6:7], v[2:3], v[6:7]
	v_pk_fma_f32 v[2:3], v[8:9], v[160:161], v[84:85] op_sel_hi:[1,0,1]
	s_nop 0
	v_mul_f32_e32 v8, 0xbfb8aa3b, v2
	v_mul_f32_e32 v9, 0xbfb8aa3b, v3
	v_exp_f32_e32 v8, v8
	v_exp_f32_e32 v9, v9
	v_add_f32_e32 v8, 1.0, v8
	v_add_f32_e32 v9, 1.0, v9
	v_rcp_f32_e32 v8, v8
	v_rcp_f32_e32 v9, v9
	s_nop 0
	v_pk_mul_f32 v[2:3], v[2:3], v[8:9]
	s_nop 0
	v_pk_mul_f32 v[8:9], v[4:5], v[2:3]
	v_cvt_pk_bf16_f32 v4, v6, v7
	v_lshrrev_b32_e32 v6, 8, v175
	v_mad_i32_i24 v6, v6, 44, v161
	v_ashrrev_i32_e32 v7, 31, v6
	v_cvt_pk_bf16_f32 v5, v8, v9
	v_lshlrev_b64 v[6:7], 15, v[6:7]
	v_lshlrev_b32_e32 v8, 7, v175
	v_lshl_add_u64 v[6:7], s[14:15], 0, v[6:7]
	v_and_b32_e32 v8, 0x7f80, v8
	v_mov_b32_e32 v9, v0
	v_lshl_add_u64 v[6:7], v[6:7], 0, v[8:9]
	v_cvt_pk_bf16_f32 v2, v10, v11
	v_cvt_pk_bf16_f32 v3, v12, v13
	v_lshl_add_u64 v[6:7], v[6:7], 0, v[130:131]
	s_mov_b64 s[14:15], s[8:9]
	global_store_dwordx4 v[6:7], v[2:5], off
	s_cbranch_vccnz .LBB0_564

.LBB0_619:
	s_lshl_b32 s5, s12, 8
	v_mov_b32_e32 v82, v159
	v_mov_b32_e32 v83, v1
	s_add_i32 s5, s5, s31
	s_nop 0
	v_add_u32_e32 v182, s5, v82
	s_lshl_b32 s5, s42, 7
	s_or_b32 s5, s5, s34
	v_lshl_add_u32 v186, v83, 3, s5
	s_ashr_i32 s5, s12, 5
	s_mul_hi_i32 s7, s5, 0x5800
	s_mulk_i32 s5, 0x5800
	s_add_u32 s14, s28, s5
	s_addc_u32 s15, s29, s7
	v_ashrrev_i32_e32 v187, 31, v186
	v_lshl_add_u64 v[86:87], v[186:187], 2, s[14:15]
	s_mov_b64 s[14:15], 0x2c00
	s_movk_i32 s5, 0x2000
	global_load_dwordx4 v[82:85], v[86:87], off offset:16
	global_load_dwordx4 v[98:101], v[86:87], off
	v_lshl_add_u64 v[88:89], v[86:87], 0, s[14:15]
	v_add_co_u32_e32 v86, vcc, s5, v86
	v_ashrrev_i32_e32 v183, 31, v182
	s_nop 0
	v_addc_co_u32_e32 v87, vcc, 0, v87, vcc
	v_lshl_add_u64 v[160:161], v[182:183], 2, s[0:1]
	global_load_dwordx4 v[102:105], v[86:87], off offset:3072
	s_nop 0
	global_load_dwordx4 v[86:89], v[88:89], off offset:16
	v_add_u32_e32 v187, 16, v182
	global_load_dword v184, v[160:161], off
	global_load_dword v180, v[160:161], off offset:64
	global_load_dword v178, v[160:161], off offset:128
	global_load_dword v176, v[160:161], off offset:192
	global_load_dword v174, v[160:161], off offset:512
	global_load_dword v172, v[160:161], off offset:576
	global_load_dword v175, v[160:161], off offset:640
	global_load_dword v160, v[160:161], off offset:704
	v_add_u32_e32 v185, 32, v182
	v_add_u32_e32 v183, 48, v182
	v_add_u32_e32 v181, 0x80, v182
	v_add_u32_e32 v179, 0x90, v182
	v_add_u32_e32 v177, 0xa0, v182
	s_waitcnt vmcnt(0)
	v_fmamk_f32 v158, v184, 0x3a800000, v223
	v_cmp_gt_f32_e32 vcc, s95, v158
	v_mul_f32_e32 v168, 0x4b800000, v158
	s_nop 0
	v_cndmask_b32_e32 v158, v158, v168, vcc
	v_rsq_f32_e32 v158, v158
	s_nop 0
	v_mul_f32_e32 v168, 0x45800000, v158
	v_cndmask_b32_e32 v184, v158, v168, vcc
	v_fmamk_f32 v158, v180, 0x3a800000, v223
	v_cmp_gt_f32_e32 vcc, s95, v158
	v_mul_f32_e32 v168, 0x4b800000, v158
	s_nop 0
	v_cndmask_b32_e32 v158, v158, v168, vcc
	v_rsq_f32_e32 v158, v158
	s_nop 0
	v_mul_f32_e32 v168, 0x45800000, v158
	v_cndmask_b32_e32 v180, v158, v168, vcc
	v_fmamk_f32 v158, v178, 0x3a800000, v223
	v_cmp_gt_f32_e32 vcc, s95, v158
	v_mul_f32_e32 v168, 0x4b800000, v158
	s_nop 0
	v_cndmask_b32_e32 v158, v158, v168, vcc
	v_rsq_f32_e32 v158, v158
	s_nop 0
	v_mul_f32_e32 v168, 0x45800000, v158
	v_cndmask_b32_e32 v178, v158, v168, vcc
	v_fmamk_f32 v158, v176, 0x3a800000, v223
	v_cmp_gt_f32_e32 vcc, s95, v158
	v_mul_f32_e32 v168, 0x4b800000, v158
	s_nop 0
	v_cndmask_b32_e32 v158, v158, v168, vcc
	v_rsq_f32_e32 v158, v158
	s_nop 0
	v_mul_f32_e32 v168, 0x45800000, v158
	v_cndmask_b32_e32 v176, v158, v168, vcc
	v_fmamk_f32 v158, v174, 0x3a800000, v223
	v_cmp_gt_f32_e32 vcc, s95, v158
	v_mul_f32_e32 v168, 0x4b800000, v158
	s_nop 0
	v_cndmask_b32_e32 v158, v158, v168, vcc
	v_rsq_f32_e32 v158, v158
	s_nop 0
	v_mul_f32_e32 v168, 0x45800000, v158
	v_cndmask_b32_e32 v174, v158, v168, vcc
	v_fmamk_f32 v158, v172, 0x3a800000, v223
	v_cmp_gt_f32_e32 vcc, s95, v158
	v_mul_f32_e32 v168, 0x4b800000, v158
	s_nop 0
	v_cndmask_b32_e32 v158, v158, v168, vcc
	v_rsq_f32_e32 v158, v158
	s_nop 0
	v_mul_f32_e32 v168, 0x45800000, v158
	v_cndmask_b32_e32 v172, v158, v168, vcc
	v_fmamk_f32 v158, v175, 0x3a800000, v223
	v_add_u32_e32 v175, 0xb0, v182
	v_cmp_gt_f32_e32 vcc, s95, v158
	v_mul_f32_e32 v168, 0x4b800000, v158
	v_fmamk_f32 v160, v160, 0x3a800000, v223
	v_cndmask_b32_e32 v158, v158, v168, vcc
	v_rsq_f32_e32 v158, v158
	v_mul_f32_e32 v161, 0x4b800000, v160
	v_mul_f32_e32 v168, 0x45800000, v158
	v_cndmask_b32_e32 v158, v158, v168, vcc
	v_cmp_gt_f32_e32 vcc, s95, v160
	v_and_b32_e32 v168, 56, v186
	s_nop 0
	v_cndmask_b32_e32 v160, v160, v161, vcc
	v_rsq_f32_e32 v160, v160
	s_nop 0
	v_mul_f32_e32 v161, 0x45800000, v160
	v_cndmask_b32_e32 v160, v160, v161, vcc
	v_ashrrev_i32_e32 v161, 6, v186
	v_pk_fma_f32 v[138:139], v[138:139], v[184:185], v[98:99] op_sel_hi:[1,0,1]
	v_pk_fma_f32 v[142:143], v[142:143], v[184:185], v[102:103] op_sel_hi:[1,0,1]
	v_mul_f32_e32 v169, 0xbfb8aa3b, v138
	v_exp_f32_e32 v169, v169
	v_pk_fma_f32 v[140:141], v[140:141], v[184:185], v[100:101] op_sel_hi:[1,0,1]
	v_pk_fma_f32 v[134:135], v[134:135], v[184:185], v[82:83] op_sel_hi:[1,0,1]
	v_pk_fma_f32 v[130:131], v[130:131], v[184:185], v[86:87] op_sel_hi:[1,0,1]
	v_add_f32_e32 v169, 1.0, v169
	v_rcp_f32_e32 v188, v169
	v_mul_f32_e32 v169, 0xbfb8aa3b, v139
	v_exp_f32_e32 v169, v169
	v_pk_fma_f32 v[132:133], v[132:133], v[184:185], v[88:89] op_sel_hi:[1,0,1]
	v_readlane_b32 s14, v254, 27
	v_readlane_b32 s15, v254, 28
	v_add_f32_e32 v169, 1.0, v169
	v_rcp_f32_e32 v189, v169
	s_nop 0
	v_pk_mul_f32 v[138:139], v[138:139], v[188:189]
	s_nop 0
	v_pk_mul_f32 v[138:139], v[142:143], v[138:139]
	v_pk_fma_f32 v[142:143], v[144:145], v[184:185], v[104:105] op_sel_hi:[1,0,1]
	v_mul_f32_e32 v144, 0xbfb8aa3b, v140
	v_mul_f32_e32 v145, 0xbfb8aa3b, v141
	v_exp_f32_e32 v144, v144
	v_exp_f32_e32 v145, v145
	v_add_f32_e32 v144, 1.0, v144
	v_add_f32_e32 v145, 1.0, v145
	v_rcp_f32_e32 v144, v144
	v_rcp_f32_e32 v145, v145
	s_nop 0
	v_pk_mul_f32 v[140:141], v[140:141], v[144:145]
	s_nop 0
	v_pk_mul_f32 v[140:141], v[142:143], v[140:141]
	v_mul_f32_e32 v142, 0xbfb8aa3b, v134
	v_mul_f32_e32 v143, 0xbfb8aa3b, v135
	v_exp_f32_e32 v142, v142
	v_exp_f32_e32 v143, v143
	v_add_f32_e32 v142, 1.0, v142
	v_add_f32_e32 v143, 1.0, v143
	v_rcp_f32_e32 v142, v142
	v_rcp_f32_e32 v143, v143
	s_nop 0
	v_pk_mul_f32 v[134:135], v[134:135], v[142:143]
	s_nop 0
	v_pk_mul_f32 v[130:131], v[130:131], v[134:135]
	v_pk_fma_f32 v[134:135], v[136:137], v[184:185], v[84:85] op_sel_hi:[1,0,1]
	s_nop 0
	v_mul_f32_e32 v136, 0xbfb8aa3b, v134
	v_mul_f32_e32 v137, 0xbfb8aa3b, v135
	v_exp_f32_e32 v136, v136
	v_exp_f32_e32 v137, v137
	v_add_f32_e32 v136, 1.0, v136
	v_add_f32_e32 v137, 1.0, v137
	v_rcp_f32_e32 v136, v136
	v_rcp_f32_e32 v137, v137
	s_nop 0
	v_pk_mul_f32 v[134:135], v[134:135], v[136:137]
	s_nop 0
	v_pk_mul_f32 v[136:137], v[132:133], v[134:135]
	v_cvt_pk_bf16_f32 v134, v130, v131
	v_lshrrev_b32_e32 v130, 8, v182
	v_mad_i32_i24 v130, v130, 44, v161
	v_ashrrev_i32_e32 v131, 31, v130
	v_cvt_pk_bf16_f32 v135, v136, v137
	v_lshlrev_b64 v[130:131], 15, v[130:131]
	v_lshlrev_b32_e32 v136, 7, v182
	v_lshl_add_u64 v[130:131], s[14:15], 0, v[130:131]
	v_and_b32_e32 v136, 0x7f80, v136
	v_mov_b32_e32 v137, v0
	v_lshl_add_u64 v[136:137], v[130:131], 0, v[136:137]
	v_lshlrev_b32_e32 v130, 1, v168
	v_mov_b32_e32 v131, v0
	v_cvt_pk_bf16_f32 v132, v138, v139
	v_cvt_pk_bf16_f32 v133, v140, v141
	v_lshl_add_u64 v[136:137], v[136:137], 0, v[130:131]
	global_store_dwordx4 v[136:137], v[132:135], off
	v_pk_fma_f32 v[126:127], v[126:127], v[180:181], v[98:99] op_sel_hi:[1,0,1]
	v_pk_fma_f32 v[122:123], v[122:123], v[180:181], v[102:103] op_sel_hi:[1,0,1]
	v_mul_f32_e32 v132, 0xbfb8aa3b, v126
	v_mul_f32_e32 v133, 0xbfb8aa3b, v127
	v_exp_f32_e32 v132, v132
	v_exp_f32_e32 v133, v133
	v_pk_fma_f32 v[124:125], v[124:125], v[180:181], v[104:105] op_sel_hi:[1,0,1]
	v_pk_fma_f32 v[118:119], v[118:119], v[180:181], v[82:83] op_sel_hi:[1,0,1]
	v_add_f32_e32 v132, 1.0, v132
	v_add_f32_e32 v133, 1.0, v133
	v_rcp_f32_e32 v132, v132
	v_rcp_f32_e32 v133, v133
	v_pk_fma_f32 v[114:115], v[114:115], v[180:181], v[86:87] op_sel_hi:[1,0,1]
	v_pk_fma_f32 v[116:117], v[116:117], v[180:181], v[88:89] op_sel_hi:[1,0,1]
	v_pk_mul_f32 v[126:127], v[126:127], v[132:133]
	s_nop 0
	v_pk_mul_f32 v[122:123], v[122:123], v[126:127]
	v_pk_fma_f32 v[126:127], v[128:129], v[180:181], v[100:101] op_sel_hi:[1,0,1]
	s_nop 0
	v_mul_f32_e32 v128, 0xbfb8aa3b, v126
	v_mul_f32_e32 v129, 0xbfb8aa3b, v127
	v_exp_f32_e32 v128, v128
	v_exp_f32_e32 v129, v129
	v_add_f32_e32 v128, 1.0, v128
	v_add_f32_e32 v129, 1.0, v129
	v_rcp_f32_e32 v128, v128
	v_rcp_f32_e32 v129, v129
	s_nop 0
	v_pk_mul_f32 v[126:127], v[126:127], v[128:129]
	s_nop 0
	v_pk_mul_f32 v[124:125], v[124:125], v[126:127]
	v_mul_f32_e32 v126, 0xbfb8aa3b, v118
	v_mul_f32_e32 v127, 0xbfb8aa3b, v119
	v_exp_f32_e32 v126, v126
	v_exp_f32_e32 v127, v127
	v_add_f32_e32 v126, 1.0, v126
	v_add_f32_e32 v127, 1.0, v127
	v_rcp_f32_e32 v126, v126
	v_rcp_f32_e32 v127, v127
	s_nop 0
	v_pk_mul_f32 v[118:119], v[118:119], v[126:127]
	s_nop 0
	v_pk_mul_f32 v[118:119], v[114:115], v[118:119]
	v_pk_fma_f32 v[114:115], v[120:121], v[180:181], v[84:85] op_sel_hi:[1,0,1]
	s_nop 0
	v_mul_f32_e32 v120, 0xbfb8aa3b, v114
	v_mul_f32_e32 v121, 0xbfb8aa3b, v115
	v_exp_f32_e32 v120, v120
	v_exp_f32_e32 v121, v121
	v_add_f32_e32 v120, 1.0, v120
	v_add_f32_e32 v121, 1.0, v121
	v_rcp_f32_e32 v120, v120
	v_rcp_f32_e32 v121, v121
	s_nop 0
	v_pk_mul_f32 v[114:115], v[114:115], v[120:121]
	s_nop 0
	v_pk_mul_f32 v[120:121], v[116:117], v[114:115]
	v_cvt_pk_bf16_f32 v116, v118, v119
	v_lshrrev_b32_e32 v118, 8, v187
	v_mad_i32_i24 v118, v118, 44, v161
	v_ashrrev_i32_e32 v119, 31, v118
	v_cvt_pk_bf16_f32 v117, v120, v121
	v_lshlrev_b64 v[118:119], 15, v[118:119]
	v_lshlrev_b32_e32 v120, 7, v187
	v_lshl_add_u64 v[118:119], s[14:15], 0, v[118:119]
	v_and_b32_e32 v120, 0x7f80, v120
	v_mov_b32_e32 v121, v0
	v_lshl_add_u64 v[118:119], v[118:119], 0, v[120:121]
	v_cvt_pk_bf16_f32 v114, v122, v123
	v_cvt_pk_bf16_f32 v115, v124, v125
	v_lshl_add_u64 v[118:119], v[118:119], 0, v[130:131]
	global_store_dwordx4 v[118:119], v[114:117], off
	v_pk_fma_f32 v[110:111], v[110:111], v[178:179], v[98:99] op_sel_hi:[1,0,1]
	v_pk_fma_f32 v[106:107], v[106:107], v[178:179], v[102:103] op_sel_hi:[1,0,1]
	v_mul_f32_e32 v114, 0xbfb8aa3b, v110
	v_mul_f32_e32 v115, 0xbfb8aa3b, v111
	v_exp_f32_e32 v114, v114
	v_exp_f32_e32 v115, v115
	v_pk_fma_f32 v[108:109], v[108:109], v[178:179], v[104:105] op_sel_hi:[1,0,1]
	v_pk_fma_f32 v[94:95], v[94:95], v[178:179], v[82:83] op_sel_hi:[1,0,1]
	v_add_f32_e32 v114, 1.0, v114
	v_add_f32_e32 v115, 1.0, v115
	v_rcp_f32_e32 v114, v114
	v_rcp_f32_e32 v115, v115
	v_pk_fma_f32 v[90:91], v[90:91], v[178:179], v[86:87] op_sel_hi:[1,0,1]
	v_pk_fma_f32 v[92:93], v[92:93], v[178:179], v[88:89] op_sel_hi:[1,0,1]
	v_pk_mul_f32 v[110:111], v[110:111], v[114:115]
	s_nop 0
	v_pk_mul_f32 v[106:107], v[106:107], v[110:111]
	v_pk_fma_f32 v[110:111], v[112:113], v[178:179], v[100:101] op_sel_hi:[1,0,1]
	s_nop 0
	v_mul_f32_e32 v112, 0xbfb8aa3b, v110
	v_mul_f32_e32 v113, 0xbfb8aa3b, v111
	v_exp_f32_e32 v112, v112
	v_exp_f32_e32 v113, v113
	v_add_f32_e32 v112, 1.0, v112
	v_add_f32_e32 v113, 1.0, v113
	v_rcp_f32_e32 v112, v112
	v_rcp_f32_e32 v113, v113
	s_nop 0
	v_pk_mul_f32 v[110:111], v[110:111], v[112:113]
	s_nop 0
	v_pk_mul_f32 v[108:109], v[108:109], v[110:111]
	v_mul_f32_e32 v110, 0xbfb8aa3b, v94
	v_mul_f32_e32 v111, 0xbfb8aa3b, v95
	v_exp_f32_e32 v110, v110
	v_exp_f32_e32 v111, v111
	v_add_f32_e32 v110, 1.0, v110
	v_add_f32_e32 v111, 1.0, v111
	v_rcp_f32_e32 v110, v110
	v_rcp_f32_e32 v111, v111
	s_nop 0
	v_pk_mul_f32 v[94:95], v[94:95], v[110:111]
	s_nop 0
	v_pk_mul_f32 v[94:95], v[90:91], v[94:95]
	v_pk_fma_f32 v[90:91], v[96:97], v[178:179], v[84:85] op_sel_hi:[1,0,1]
	s_nop 0
	v_mul_f32_e32 v96, 0xbfb8aa3b, v90
	v_mul_f32_e32 v97, 0xbfb8aa3b, v91
	v_exp_f32_e32 v96, v96
	v_exp_f32_e32 v97, v97
	v_add_f32_e32 v96, 1.0, v96
	v_add_f32_e32 v97, 1.0, v97
	v_rcp_f32_e32 v96, v96
	v_rcp_f32_e32 v97, v97
	s_nop 0
	v_pk_mul_f32 v[90:91], v[90:91], v[96:97]
	s_nop 0
	v_pk_mul_f32 v[96:97], v[92:93], v[90:91]
	v_cvt_pk_bf16_f32 v92, v94, v95
	v_lshrrev_b32_e32 v94, 8, v185
	v_mad_i32_i24 v94, v94, 44, v161
	v_ashrrev_i32_e32 v95, 31, v94
	v_cvt_pk_bf16_f32 v93, v96, v97
	v_lshlrev_b64 v[94:95], 15, v[94:95]
	v_lshlrev_b32_e32 v96, 7, v185
	v_lshl_add_u64 v[94:95], s[14:15], 0, v[94:95]
	v_and_b32_e32 v96, 0x7f80, v96
	v_mov_b32_e32 v97, v0
	v_lshl_add_u64 v[94:95], v[94:95], 0, v[96:97]
	v_cvt_pk_bf16_f32 v90, v106, v107
	v_cvt_pk_bf16_f32 v91, v108, v109
	v_lshl_add_u64 v[94:95], v[94:95], 0, v[130:131]
	global_store_dwordx4 v[94:95], v[90:93], off
	v_pk_fma_f32 v[78:79], v[78:79], v[176:177], v[98:99] op_sel_hi:[1,0,1]
	v_pk_fma_f32 v[74:75], v[74:75], v[176:177], v[102:103] op_sel_hi:[1,0,1]
	v_mul_f32_e32 v90, 0xbfb8aa3b, v78
	v_mul_f32_e32 v91, 0xbfb8aa3b, v79
	v_exp_f32_e32 v90, v90
	v_exp_f32_e32 v91, v91
	v_pk_fma_f32 v[76:77], v[76:77], v[176:177], v[104:105] op_sel_hi:[1,0,1]
	v_pk_fma_f32 v[70:71], v[70:71], v[176:177], v[82:83] op_sel_hi:[1,0,1]
	v_add_f32_e32 v90, 1.0, v90
	v_add_f32_e32 v91, 1.0, v91
	v_rcp_f32_e32 v90, v90
	v_rcp_f32_e32 v91, v91
	v_pk_fma_f32 v[66:67], v[66:67], v[176:177], v[86:87] op_sel_hi:[1,0,1]
	v_pk_fma_f32 v[68:69], v[68:69], v[176:177], v[88:89] op_sel_hi:[1,0,1]
	v_pk_mul_f32 v[78:79], v[78:79], v[90:91]
	s_nop 0
	v_pk_mul_f32 v[74:75], v[74:75], v[78:79]
	v_pk_fma_f32 v[78:79], v[80:81], v[176:177], v[100:101] op_sel_hi:[1,0,1]
	s_nop 0
	v_mul_f32_e32 v80, 0xbfb8aa3b, v78
	v_mul_f32_e32 v81, 0xbfb8aa3b, v79
	v_exp_f32_e32 v80, v80
	v_exp_f32_e32 v81, v81
	v_add_f32_e32 v80, 1.0, v80
	v_add_f32_e32 v81, 1.0, v81
	v_rcp_f32_e32 v80, v80
	v_rcp_f32_e32 v81, v81
	s_nop 0
	v_pk_mul_f32 v[78:79], v[78:79], v[80:81]
	s_nop 0
	v_pk_mul_f32 v[76:77], v[76:77], v[78:79]
	v_mul_f32_e32 v78, 0xbfb8aa3b, v70
	v_mul_f32_e32 v79, 0xbfb8aa3b, v71
	v_exp_f32_e32 v78, v78
	v_exp_f32_e32 v79, v79
	v_add_f32_e32 v78, 1.0, v78
	v_add_f32_e32 v79, 1.0, v79
	v_rcp_f32_e32 v78, v78
	v_rcp_f32_e32 v79, v79
	s_nop 0
	v_pk_mul_f32 v[70:71], v[70:71], v[78:79]
	s_nop 0
	v_pk_mul_f32 v[70:71], v[66:67], v[70:71]
	v_pk_fma_f32 v[66:67], v[72:73], v[176:177], v[84:85] op_sel_hi:[1,0,1]
	s_nop 0
	v_mul_f32_e32 v72, 0xbfb8aa3b, v66
	v_mul_f32_e32 v73, 0xbfb8aa3b, v67
	v_exp_f32_e32 v72, v72
	v_exp_f32_e32 v73, v73
	v_add_f32_e32 v72, 1.0, v72
	v_add_f32_e32 v73, 1.0, v73
	v_rcp_f32_e32 v72, v72
	v_rcp_f32_e32 v73, v73
	s_nop 0
	v_pk_mul_f32 v[66:67], v[66:67], v[72:73]
	s_nop 0
	v_pk_mul_f32 v[72:73], v[68:69], v[66:67]
	v_cvt_pk_bf16_f32 v68, v70, v71
	v_lshrrev_b32_e32 v70, 8, v183
	v_mad_i32_i24 v70, v70, 44, v161
	v_ashrrev_i32_e32 v71, 31, v70
	v_cvt_pk_bf16_f32 v69, v72, v73
	v_lshlrev_b64 v[70:71], 15, v[70:71]
	v_lshlrev_b32_e32 v72, 7, v183
	v_lshl_add_u64 v[70:71], s[14:15], 0, v[70:71]
	v_and_b32_e32 v72, 0x7f80, v72
	v_mov_b32_e32 v73, v0
	v_lshl_add_u64 v[70:71], v[70:71], 0, v[72:73]
	v_cvt_pk_bf16_f32 v66, v74, v75
	v_cvt_pk_bf16_f32 v67, v76, v77
	v_lshl_add_u64 v[70:71], v[70:71], 0, v[130:131]
	global_store_dwordx4 v[70:71], v[66:69], off
	v_pk_fma_f32 v[62:63], v[62:63], v[174:175], v[98:99] op_sel_hi:[1,0,1]
	v_pk_fma_f32 v[58:59], v[58:59], v[174:175], v[102:103] op_sel_hi:[1,0,1]
	v_mul_f32_e32 v66, 0xbfb8aa3b, v62
	v_mul_f32_e32 v67, 0xbfb8aa3b, v63
	v_exp_f32_e32 v66, v66
	v_exp_f32_e32 v67, v67
	v_pk_fma_f32 v[60:61], v[60:61], v[174:175], v[104:105] op_sel_hi:[1,0,1]
	v_pk_fma_f32 v[54:55], v[54:55], v[174:175], v[82:83] op_sel_hi:[1,0,1]
	v_add_f32_e32 v66, 1.0, v66
	v_add_f32_e32 v67, 1.0, v67
	v_rcp_f32_e32 v66, v66
	v_rcp_f32_e32 v67, v67
	v_pk_fma_f32 v[50:51], v[50:51], v[174:175], v[86:87] op_sel_hi:[1,0,1]
	v_pk_fma_f32 v[52:53], v[52:53], v[174:175], v[88:89] op_sel_hi:[1,0,1]
	v_pk_mul_f32 v[62:63], v[62:63], v[66:67]
	s_nop 0
	v_pk_mul_f32 v[58:59], v[58:59], v[62:63]
	v_pk_fma_f32 v[62:63], v[64:65], v[174:175], v[100:101] op_sel_hi:[1,0,1]
	s_nop 0
	v_mul_f32_e32 v64, 0xbfb8aa3b, v62
	v_mul_f32_e32 v65, 0xbfb8aa3b, v63
	v_exp_f32_e32 v64, v64
	v_exp_f32_e32 v65, v65
	v_add_f32_e32 v64, 1.0, v64
	v_add_f32_e32 v65, 1.0, v65
	v_rcp_f32_e32 v64, v64
	v_rcp_f32_e32 v65, v65
	s_nop 0
	v_pk_mul_f32 v[62:63], v[62:63], v[64:65]
	s_nop 0
	v_pk_mul_f32 v[60:61], v[60:61], v[62:63]
	v_mul_f32_e32 v62, 0xbfb8aa3b, v54
	v_mul_f32_e32 v63, 0xbfb8aa3b, v55
	v_exp_f32_e32 v62, v62
	v_exp_f32_e32 v63, v63
	v_add_f32_e32 v62, 1.0, v62
	v_add_f32_e32 v63, 1.0, v63
	v_rcp_f32_e32 v62, v62
	v_rcp_f32_e32 v63, v63
	s_nop 0
	v_pk_mul_f32 v[54:55], v[54:55], v[62:63]
	s_nop 0
	v_pk_mul_f32 v[54:55], v[50:51], v[54:55]
	v_pk_fma_f32 v[50:51], v[56:57], v[174:175], v[84:85] op_sel_hi:[1,0,1]
	s_nop 0
	v_mul_f32_e32 v56, 0xbfb8aa3b, v50
	v_mul_f32_e32 v57, 0xbfb8aa3b, v51
	v_exp_f32_e32 v56, v56
	v_exp_f32_e32 v57, v57
	v_add_f32_e32 v56, 1.0, v56
	v_add_f32_e32 v57, 1.0, v57
	v_rcp_f32_e32 v56, v56
	v_rcp_f32_e32 v57, v57
	s_nop 0
	v_pk_mul_f32 v[50:51], v[50:51], v[56:57]
	s_nop 0
	v_pk_mul_f32 v[56:57], v[52:53], v[50:51]
	v_cvt_pk_bf16_f32 v52, v54, v55
	v_lshrrev_b32_e32 v54, 8, v181
	v_mad_i32_i24 v54, v54, 44, v161
	v_ashrrev_i32_e32 v55, 31, v54
	v_cvt_pk_bf16_f32 v53, v56, v57
	v_lshlrev_b64 v[54:55], 15, v[54:55]
	v_lshlrev_b32_e32 v56, 7, v181
	v_lshl_add_u64 v[54:55], s[14:15], 0, v[54:55]
	v_and_b32_e32 v56, 0x7f80, v56
	v_mov_b32_e32 v57, v0
	v_lshl_add_u64 v[54:55], v[54:55], 0, v[56:57]
	v_cvt_pk_bf16_f32 v50, v58, v59
	v_cvt_pk_bf16_f32 v51, v60, v61
	v_lshl_add_u64 v[54:55], v[54:55], 0, v[130:131]
	global_store_dwordx4 v[54:55], v[50:53], off
	v_pk_fma_f32 v[46:47], v[46:47], v[172:173], v[98:99] op_sel_hi:[1,0,1]
	v_pk_fma_f32 v[42:43], v[42:43], v[172:173], v[102:103] op_sel_hi:[1,0,1]
	v_mul_f32_e32 v50, 0xbfb8aa3b, v46
	v_mul_f32_e32 v51, 0xbfb8aa3b, v47
	v_exp_f32_e32 v50, v50
	v_exp_f32_e32 v51, v51
	v_pk_fma_f32 v[44:45], v[44:45], v[172:173], v[104:105] op_sel_hi:[1,0,1]
	v_pk_fma_f32 v[38:39], v[38:39], v[172:173], v[82:83] op_sel_hi:[1,0,1]
	v_add_f32_e32 v50, 1.0, v50
	v_add_f32_e32 v51, 1.0, v51
	v_rcp_f32_e32 v50, v50
	v_rcp_f32_e32 v51, v51
	v_pk_fma_f32 v[34:35], v[34:35], v[172:173], v[86:87] op_sel_hi:[1,0,1]
	v_pk_fma_f32 v[36:37], v[36:37], v[172:173], v[88:89] op_sel_hi:[1,0,1]
	v_pk_mul_f32 v[46:47], v[46:47], v[50:51]
	s_nop 0
	v_pk_mul_f32 v[42:43], v[42:43], v[46:47]
	v_pk_fma_f32 v[46:47], v[48:49], v[172:173], v[100:101] op_sel_hi:[1,0,1]
	s_nop 0
	v_mul_f32_e32 v48, 0xbfb8aa3b, v46
	v_mul_f32_e32 v49, 0xbfb8aa3b, v47
	v_exp_f32_e32 v48, v48
	v_exp_f32_e32 v49, v49
	v_add_f32_e32 v48, 1.0, v48
	v_add_f32_e32 v49, 1.0, v49
	v_rcp_f32_e32 v48, v48
	v_rcp_f32_e32 v49, v49
	s_nop 0
	v_pk_mul_f32 v[46:47], v[46:47], v[48:49]
	s_nop 0
	v_pk_mul_f32 v[44:45], v[44:45], v[46:47]
	v_mul_f32_e32 v46, 0xbfb8aa3b, v38
	v_mul_f32_e32 v47, 0xbfb8aa3b, v39
	v_exp_f32_e32 v46, v46
	v_exp_f32_e32 v47, v47
	v_add_f32_e32 v46, 1.0, v46
	v_add_f32_e32 v47, 1.0, v47
	v_rcp_f32_e32 v46, v46
	v_rcp_f32_e32 v47, v47
	s_nop 0
	v_pk_mul_f32 v[38:39], v[38:39], v[46:47]
	s_nop 0
	v_pk_mul_f32 v[38:39], v[34:35], v[38:39]
	v_pk_fma_f32 v[34:35], v[40:41], v[172:173], v[84:85] op_sel_hi:[1,0,1]
	s_nop 0
	v_mul_f32_e32 v40, 0xbfb8aa3b, v34
	v_mul_f32_e32 v41, 0xbfb8aa3b, v35
	v_exp_f32_e32 v40, v40
	v_exp_f32_e32 v41, v41
	v_add_f32_e32 v40, 1.0, v40
	v_add_f32_e32 v41, 1.0, v41
	v_rcp_f32_e32 v40, v40
	v_rcp_f32_e32 v41, v41
	s_nop 0
	v_pk_mul_f32 v[34:35], v[34:35], v[40:41]
	s_nop 0
	v_pk_mul_f32 v[40:41], v[36:37], v[34:35]
	v_cvt_pk_bf16_f32 v36, v38, v39
	v_lshrrev_b32_e32 v38, 8, v179
	v_mad_i32_i24 v38, v38, 44, v161
	v_ashrrev_i32_e32 v39, 31, v38
	v_cvt_pk_bf16_f32 v37, v40, v41
	v_lshlrev_b64 v[38:39], 15, v[38:39]
	v_lshlrev_b32_e32 v40, 7, v179
	v_lshl_add_u64 v[38:39], s[14:15], 0, v[38:39]
	v_and_b32_e32 v40, 0x7f80, v40
	v_mov_b32_e32 v41, v0
	v_lshl_add_u64 v[38:39], v[38:39], 0, v[40:41]
	v_cvt_pk_bf16_f32 v34, v42, v43
	v_cvt_pk_bf16_f32 v35, v44, v45
	v_lshl_add_u64 v[38:39], v[38:39], 0, v[130:131]
	global_store_dwordx4 v[38:39], v[34:37], off
	v_pk_fma_f32 v[30:31], v[30:31], v[158:159], v[98:99] op_sel_hi:[1,0,1]
	v_pk_fma_f32 v[26:27], v[26:27], v[158:159], v[102:103] op_sel_hi:[1,0,1]
	v_mul_f32_e32 v34, 0xbfb8aa3b, v30
	v_mul_f32_e32 v35, 0xbfb8aa3b, v31
	v_exp_f32_e32 v34, v34
	v_exp_f32_e32 v35, v35
	v_pk_fma_f32 v[28:29], v[28:29], v[158:159], v[104:105] op_sel_hi:[1,0,1]
	v_pk_fma_f32 v[22:23], v[22:23], v[158:159], v[82:83] op_sel_hi:[1,0,1]
	v_add_f32_e32 v34, 1.0, v34
	v_add_f32_e32 v35, 1.0, v35
	v_rcp_f32_e32 v34, v34
	v_rcp_f32_e32 v35, v35
	v_pk_fma_f32 v[18:19], v[18:19], v[158:159], v[86:87] op_sel_hi:[1,0,1]
	v_pk_fma_f32 v[20:21], v[20:21], v[158:159], v[88:89] op_sel_hi:[1,0,1]
	v_pk_mul_f32 v[30:31], v[30:31], v[34:35]
	s_nop 0
	v_pk_mul_f32 v[26:27], v[26:27], v[30:31]
	v_pk_fma_f32 v[30:31], v[32:33], v[158:159], v[100:101] op_sel_hi:[1,0,1]
	s_nop 0
	v_mul_f32_e32 v32, 0xbfb8aa3b, v30
	v_mul_f32_e32 v33, 0xbfb8aa3b, v31
	v_exp_f32_e32 v32, v32
	v_exp_f32_e32 v33, v33
	v_add_f32_e32 v32, 1.0, v32
	v_add_f32_e32 v33, 1.0, v33
	v_rcp_f32_e32 v32, v32
	v_rcp_f32_e32 v33, v33
	s_nop 0
	v_pk_mul_f32 v[30:31], v[30:31], v[32:33]
	s_nop 0
	v_pk_mul_f32 v[28:29], v[28:29], v[30:31]
	v_mul_f32_e32 v30, 0xbfb8aa3b, v22
	v_mul_f32_e32 v31, 0xbfb8aa3b, v23
	v_exp_f32_e32 v30, v30
	v_exp_f32_e32 v31, v31
	v_add_f32_e32 v30, 1.0, v30
	v_add_f32_e32 v31, 1.0, v31
	v_rcp_f32_e32 v30, v30
	v_rcp_f32_e32 v31, v31
	s_nop 0
	v_pk_mul_f32 v[22:23], v[22:23], v[30:31]
	s_nop 0
	v_pk_mul_f32 v[22:23], v[18:19], v[22:23]
	v_pk_fma_f32 v[18:19], v[24:25], v[158:159], v[84:85] op_sel_hi:[1,0,1]
	s_nop 0
	v_mul_f32_e32 v24, 0xbfb8aa3b, v18
	v_mul_f32_e32 v25, 0xbfb8aa3b, v19
	v_exp_f32_e32 v24, v24
	v_exp_f32_e32 v25, v25
	v_add_f32_e32 v24, 1.0, v24
	v_add_f32_e32 v25, 1.0, v25
	v_rcp_f32_e32 v24, v24
	v_rcp_f32_e32 v25, v25
	s_nop 0
	v_pk_mul_f32 v[18:19], v[18:19], v[24:25]
	s_nop 0
	v_pk_mul_f32 v[24:25], v[20:21], v[18:19]
	v_cvt_pk_bf16_f32 v20, v22, v23
	v_lshrrev_b32_e32 v22, 8, v177
	v_mad_i32_i24 v22, v22, 44, v161
	v_ashrrev_i32_e32 v23, 31, v22
	v_cvt_pk_bf16_f32 v21, v24, v25
	v_lshlrev_b64 v[22:23], 15, v[22:23]
	v_lshlrev_b32_e32 v24, 7, v177
	v_lshl_add_u64 v[22:23], s[14:15], 0, v[22:23]
	v_and_b32_e32 v24, 0x7f80, v24
	v_mov_b32_e32 v25, v0
	v_lshl_add_u64 v[22:23], v[22:23], 0, v[24:25]
	v_cvt_pk_bf16_f32 v18, v26, v27
	v_cvt_pk_bf16_f32 v19, v28, v29
	v_lshl_add_u64 v[22:23], v[22:23], 0, v[130:131]
	global_store_dwordx4 v[22:23], v[18:21], off
	v_pk_fma_f32 v[14:15], v[14:15], v[160:161], v[98:99] op_sel_hi:[1,0,1]
	v_pk_fma_f32 v[10:11], v[10:11], v[160:161], v[102:103] op_sel_hi:[1,0,1]
	v_mul_f32_e32 v18, 0xbfb8aa3b, v14
	v_mul_f32_e32 v19, 0xbfb8aa3b, v15
	v_exp_f32_e32 v18, v18
	v_exp_f32_e32 v19, v19
	v_pk_fma_f32 v[12:13], v[12:13], v[160:161], v[104:105] op_sel_hi:[1,0,1]
	v_pk_fma_f32 v[6:7], v[6:7], v[160:161], v[82:83] op_sel_hi:[1,0,1]
	v_add_f32_e32 v18, 1.0, v18
	v_add_f32_e32 v19, 1.0, v19
	v_rcp_f32_e32 v18, v18
	v_rcp_f32_e32 v19, v19
	v_pk_fma_f32 v[2:3], v[2:3], v[160:161], v[86:87] op_sel_hi:[1,0,1]
	v_pk_fma_f32 v[4:5], v[4:5], v[160:161], v[88:89] op_sel_hi:[1,0,1]
	s_and_b64 vcc, exec, s[36:37]
	v_pk_mul_f32 v[14:15], v[14:15], v[18:19]
	s_mov_b32 s42, s4
	v_pk_mul_f32 v[10:11], v[10:11], v[14:15]
	v_pk_fma_f32 v[14:15], v[16:17], v[160:161], v[100:101] op_sel_hi:[1,0,1]
	s_mov_b32 s12, s6
	v_mul_f32_e32 v16, 0xbfb8aa3b, v14
	v_mul_f32_e32 v17, 0xbfb8aa3b, v15
	v_exp_f32_e32 v16, v16
	v_exp_f32_e32 v17, v17
	s_mov_b64 s[16:17], s[10:11]
	v_add_f32_e32 v16, 1.0, v16
	v_add_f32_e32 v17, 1.0, v17
	v_rcp_f32_e32 v16, v16
	v_rcp_f32_e32 v17, v17
	s_nop 0
	v_pk_mul_f32 v[14:15], v[14:15], v[16:17]
	s_nop 0
	v_pk_mul_f32 v[12:13], v[12:13], v[14:15]
	v_mul_f32_e32 v14, 0xbfb8aa3b, v6
	v_mul_f32_e32 v15, 0xbfb8aa3b, v7
	v_exp_f32_e32 v14, v14
	v_exp_f32_e32 v15, v15
	v_add_f32_e32 v14, 1.0, v14
	v_add_f32_e32 v15, 1.0, v15
	v_rcp_f32_e32 v14, v14
	v_rcp_f32_e32 v15, v15
	s_nop 0
	v_pk_mul_f32 v[6:7], v[6:7], v[14:15]
	s_nop 0
	v_pk_mul_f32 v[6:7], v[2:3], v[6:7]
	v_pk_fma_f32 v[2:3], v[8:9], v[160:161], v[84:85] op_sel_hi:[1,0,1]
	s_nop 0
	v_mul_f32_e32 v8, 0xbfb8aa3b, v2
	v_mul_f32_e32 v9, 0xbfb8aa3b, v3
	v_exp_f32_e32 v8, v8
	v_exp_f32_e32 v9, v9
	v_add_f32_e32 v8, 1.0, v8
	v_add_f32_e32 v9, 1.0, v9
	v_rcp_f32_e32 v8, v8
	v_rcp_f32_e32 v9, v9
	s_nop 0
	v_pk_mul_f32 v[2:3], v[2:3], v[8:9]
	s_nop 0
	v_pk_mul_f32 v[8:9], v[4:5], v[2:3]
	v_cvt_pk_bf16_f32 v4, v6, v7
	v_lshrrev_b32_e32 v6, 8, v175
	v_mad_i32_i24 v6, v6, 44, v161
	v_ashrrev_i32_e32 v7, 31, v6
	v_cvt_pk_bf16_f32 v5, v8, v9
	v_lshlrev_b64 v[6:7], 15, v[6:7]
	v_lshlrev_b32_e32 v8, 7, v175
	v_lshl_add_u64 v[6:7], s[14:15], 0, v[6:7]
	v_and_b32_e32 v8, 0x7f80, v8
	v_mov_b32_e32 v9, v0
	v_lshl_add_u64 v[6:7], v[6:7], 0, v[8:9]
	v_cvt_pk_bf16_f32 v2, v10, v11
	v_cvt_pk_bf16_f32 v3, v12, v13
	v_lshl_add_u64 v[6:7], v[6:7], 0, v[130:131]
	s_mov_b64 s[14:15], s[8:9]
	global_store_dwordx4 v[6:7], v[2:5], off
	s_cbranch_vccnz .LBB0_625

.LBB0_869:
	s_lshl_b32 s3, s10, 8
	v_mov_b32_e32 v82, v159
	v_mov_b32_e32 v83, v1
	s_add_i32 s3, s3, s27
	v_readlane_b32 s12, v254, 33
	v_add_u32_e32 v182, s3, v82
	s_lshl_b32 s3, s38, 7
	s_or_b32 s3, s3, s28
	v_lshl_add_u32 v186, v83, 3, s3
	s_ashr_i32 s3, s10, 5
	s_mul_hi_i32 s5, s3, 0x5800
	s_mulk_i32 s3, 0x5800
	v_readlane_b32 s13, v254, 34
	s_add_u32 s12, s12, s3
	s_addc_u32 s13, s13, s5
	v_ashrrev_i32_e32 v187, 31, v186
	v_lshl_add_u64 v[86:87], v[186:187], 2, s[12:13]
	s_mov_b64 s[12:13], 0x2c00
	v_lshl_add_u64 v[88:89], v[86:87], 0, s[12:13]
	s_movk_i32 s3, 0x2000
	v_readlane_b32 s12, v254, 31
	global_load_dwordx4 v[82:85], v[86:87], off offset:16
	global_load_dwordx4 v[98:101], v[86:87], off
	v_add_co_u32_e32 v86, vcc, s3, v86
	v_ashrrev_i32_e32 v183, 31, v182
	v_readlane_b32 s13, v254, 32
	v_addc_co_u32_e32 v87, vcc, 0, v87, vcc
	s_nop 0
	v_lshl_add_u64 v[160:161], v[182:183], 2, s[12:13]
	global_load_dwordx4 v[102:105], v[86:87], off offset:3072
	s_nop 0
	global_load_dwordx4 v[86:89], v[88:89], off offset:16
	v_add_u32_e32 v187, 16, v182
	global_load_dword v184, v[160:161], off
	global_load_dword v180, v[160:161], off offset:64
	global_load_dword v178, v[160:161], off offset:128
	global_load_dword v176, v[160:161], off offset:192
	global_load_dword v174, v[160:161], off offset:512
	global_load_dword v172, v[160:161], off offset:576
	global_load_dword v175, v[160:161], off offset:640
	global_load_dword v160, v[160:161], off offset:704
	v_add_u32_e32 v185, 32, v182
	v_add_u32_e32 v183, 48, v182
	v_add_u32_e32 v181, 0x80, v182
	v_add_u32_e32 v179, 0x90, v182
	v_add_u32_e32 v177, 0xa0, v182
	s_waitcnt vmcnt(0)
	v_fmamk_f32 v158, v184, 0x3a800000, v223
	v_cmp_gt_f32_e32 vcc, s95, v158
	v_mul_f32_e32 v168, 0x4b800000, v158
	s_nop 0
	v_cndmask_b32_e32 v158, v158, v168, vcc
	v_rsq_f32_e32 v158, v158
	s_nop 0
	v_mul_f32_e32 v168, 0x45800000, v158
	v_cndmask_b32_e32 v184, v158, v168, vcc
	v_fmamk_f32 v158, v180, 0x3a800000, v223
	v_cmp_gt_f32_e32 vcc, s95, v158
	v_mul_f32_e32 v168, 0x4b800000, v158
	s_nop 0
	v_cndmask_b32_e32 v158, v158, v168, vcc
	v_rsq_f32_e32 v158, v158
	s_nop 0
	v_mul_f32_e32 v168, 0x45800000, v158
	v_cndmask_b32_e32 v180, v158, v168, vcc
	v_fmamk_f32 v158, v178, 0x3a800000, v223
	v_cmp_gt_f32_e32 vcc, s95, v158
	v_mul_f32_e32 v168, 0x4b800000, v158
	s_nop 0
	v_cndmask_b32_e32 v158, v158, v168, vcc
	v_rsq_f32_e32 v158, v158
	s_nop 0
	v_mul_f32_e32 v168, 0x45800000, v158
	v_cndmask_b32_e32 v178, v158, v168, vcc
	v_fmamk_f32 v158, v176, 0x3a800000, v223
	v_cmp_gt_f32_e32 vcc, s95, v158
	v_mul_f32_e32 v168, 0x4b800000, v158
	s_nop 0
	v_cndmask_b32_e32 v158, v158, v168, vcc
	v_rsq_f32_e32 v158, v158
	s_nop 0
	v_mul_f32_e32 v168, 0x45800000, v158
	v_cndmask_b32_e32 v176, v158, v168, vcc
	v_fmamk_f32 v158, v174, 0x3a800000, v223
	v_cmp_gt_f32_e32 vcc, s95, v158
	v_mul_f32_e32 v168, 0x4b800000, v158
	s_nop 0
	v_cndmask_b32_e32 v158, v158, v168, vcc
	v_rsq_f32_e32 v158, v158
	s_nop 0
	v_mul_f32_e32 v168, 0x45800000, v158
	v_cndmask_b32_e32 v174, v158, v168, vcc
	v_fmamk_f32 v158, v172, 0x3a800000, v223
	v_cmp_gt_f32_e32 vcc, s95, v158
	v_mul_f32_e32 v168, 0x4b800000, v158
	s_nop 0
	v_cndmask_b32_e32 v158, v158, v168, vcc
	v_rsq_f32_e32 v158, v158
	s_nop 0
	v_mul_f32_e32 v168, 0x45800000, v158
	v_cndmask_b32_e32 v172, v158, v168, vcc
	v_fmamk_f32 v158, v175, 0x3a800000, v223
	v_add_u32_e32 v175, 0xb0, v182
	v_cmp_gt_f32_e32 vcc, s95, v158
	v_mul_f32_e32 v168, 0x4b800000, v158
	v_fmamk_f32 v160, v160, 0x3a800000, v223
	v_cndmask_b32_e32 v158, v158, v168, vcc
	v_rsq_f32_e32 v158, v158
	v_mul_f32_e32 v161, 0x4b800000, v160
	v_mul_f32_e32 v168, 0x45800000, v158
	v_cndmask_b32_e32 v158, v158, v168, vcc
	v_cmp_gt_f32_e32 vcc, s95, v160
	v_and_b32_e32 v168, 56, v186
	s_nop 0
	v_cndmask_b32_e32 v160, v160, v161, vcc
	v_rsq_f32_e32 v160, v160
	s_nop 0
	v_mul_f32_e32 v161, 0x45800000, v160
	v_cndmask_b32_e32 v160, v160, v161, vcc
	v_ashrrev_i32_e32 v161, 6, v186
	v_pk_fma_f32 v[138:139], v[138:139], v[184:185], v[98:99] op_sel_hi:[1,0,1]
	v_pk_fma_f32 v[142:143], v[142:143], v[184:185], v[102:103] op_sel_hi:[1,0,1]
	v_mul_f32_e32 v169, 0xbfb8aa3b, v138
	v_exp_f32_e32 v169, v169
	v_pk_fma_f32 v[140:141], v[140:141], v[184:185], v[100:101] op_sel_hi:[1,0,1]
	v_pk_fma_f32 v[134:135], v[134:135], v[184:185], v[82:83] op_sel_hi:[1,0,1]
	v_pk_fma_f32 v[130:131], v[130:131], v[184:185], v[86:87] op_sel_hi:[1,0,1]
	v_add_f32_e32 v169, 1.0, v169
	v_rcp_f32_e32 v188, v169
	v_mul_f32_e32 v169, 0xbfb8aa3b, v139
	v_exp_f32_e32 v169, v169
	v_pk_fma_f32 v[132:133], v[132:133], v[184:185], v[88:89] op_sel_hi:[1,0,1]
	v_readlane_b32 s12, v254, 27
	v_readlane_b32 s13, v254, 28
	v_add_f32_e32 v169, 1.0, v169
	v_rcp_f32_e32 v189, v169
	s_nop 0
	v_pk_mul_f32 v[138:139], v[138:139], v[188:189]
	s_nop 0
	v_pk_mul_f32 v[138:139], v[142:143], v[138:139]
	v_pk_fma_f32 v[142:143], v[144:145], v[184:185], v[104:105] op_sel_hi:[1,0,1]
	v_mul_f32_e32 v144, 0xbfb8aa3b, v140
	v_mul_f32_e32 v145, 0xbfb8aa3b, v141
	v_exp_f32_e32 v144, v144
	v_exp_f32_e32 v145, v145
	v_add_f32_e32 v144, 1.0, v144
	v_add_f32_e32 v145, 1.0, v145
	v_rcp_f32_e32 v144, v144
	v_rcp_f32_e32 v145, v145
	s_nop 0
	v_pk_mul_f32 v[140:141], v[140:141], v[144:145]
	s_nop 0
	v_pk_mul_f32 v[140:141], v[142:143], v[140:141]
	v_mul_f32_e32 v142, 0xbfb8aa3b, v134
	v_mul_f32_e32 v143, 0xbfb8aa3b, v135
	v_exp_f32_e32 v142, v142
	v_exp_f32_e32 v143, v143
	v_add_f32_e32 v142, 1.0, v142
	v_add_f32_e32 v143, 1.0, v143
	v_rcp_f32_e32 v142, v142
	v_rcp_f32_e32 v143, v143
	s_nop 0
	v_pk_mul_f32 v[134:135], v[134:135], v[142:143]
	s_nop 0
	v_pk_mul_f32 v[130:131], v[130:131], v[134:135]
	v_pk_fma_f32 v[134:135], v[136:137], v[184:185], v[84:85] op_sel_hi:[1,0,1]
	s_nop 0
	v_mul_f32_e32 v136, 0xbfb8aa3b, v134
	v_mul_f32_e32 v137, 0xbfb8aa3b, v135
	v_exp_f32_e32 v136, v136
	v_exp_f32_e32 v137, v137
	v_add_f32_e32 v136, 1.0, v136
	v_add_f32_e32 v137, 1.0, v137
	v_rcp_f32_e32 v136, v136
	v_rcp_f32_e32 v137, v137
	s_nop 0
	v_pk_mul_f32 v[134:135], v[134:135], v[136:137]
	s_nop 0
	v_pk_mul_f32 v[136:137], v[132:133], v[134:135]
	v_cvt_pk_bf16_f32 v134, v130, v131
	v_lshrrev_b32_e32 v130, 8, v182
	v_mad_i32_i24 v130, v130, 44, v161
	v_ashrrev_i32_e32 v131, 31, v130
	v_cvt_pk_bf16_f32 v135, v136, v137
	v_lshlrev_b64 v[130:131], 15, v[130:131]
	v_lshlrev_b32_e32 v136, 7, v182
	v_lshl_add_u64 v[130:131], s[12:13], 0, v[130:131]
	v_and_b32_e32 v136, 0x7f80, v136
	v_mov_b32_e32 v137, v0
	v_lshl_add_u64 v[136:137], v[130:131], 0, v[136:137]
	v_lshlrev_b32_e32 v130, 1, v168
	v_mov_b32_e32 v131, v0
	v_cvt_pk_bf16_f32 v132, v138, v139
	v_cvt_pk_bf16_f32 v133, v140, v141
	v_lshl_add_u64 v[136:137], v[136:137], 0, v[130:131]
	global_store_dwordx4 v[136:137], v[132:135], off
	v_pk_fma_f32 v[126:127], v[126:127], v[180:181], v[98:99] op_sel_hi:[1,0,1]
	v_pk_fma_f32 v[122:123], v[122:123], v[180:181], v[102:103] op_sel_hi:[1,0,1]
	v_mul_f32_e32 v132, 0xbfb8aa3b, v126
	v_mul_f32_e32 v133, 0xbfb8aa3b, v127
	v_exp_f32_e32 v132, v132
	v_exp_f32_e32 v133, v133
	v_pk_fma_f32 v[124:125], v[124:125], v[180:181], v[104:105] op_sel_hi:[1,0,1]
	v_pk_fma_f32 v[118:119], v[118:119], v[180:181], v[82:83] op_sel_hi:[1,0,1]
	v_add_f32_e32 v132, 1.0, v132
	v_add_f32_e32 v133, 1.0, v133
	v_rcp_f32_e32 v132, v132
	v_rcp_f32_e32 v133, v133
	v_pk_fma_f32 v[114:115], v[114:115], v[180:181], v[86:87] op_sel_hi:[1,0,1]
	v_pk_fma_f32 v[116:117], v[116:117], v[180:181], v[88:89] op_sel_hi:[1,0,1]
	v_pk_mul_f32 v[126:127], v[126:127], v[132:133]
	s_nop 0
	v_pk_mul_f32 v[122:123], v[122:123], v[126:127]
	v_pk_fma_f32 v[126:127], v[128:129], v[180:181], v[100:101] op_sel_hi:[1,0,1]
	s_nop 0
	v_mul_f32_e32 v128, 0xbfb8aa3b, v126
	v_mul_f32_e32 v129, 0xbfb8aa3b, v127
	v_exp_f32_e32 v128, v128
	v_exp_f32_e32 v129, v129
	v_add_f32_e32 v128, 1.0, v128
	v_add_f32_e32 v129, 1.0, v129
	v_rcp_f32_e32 v128, v128
	v_rcp_f32_e32 v129, v129
	s_nop 0
	v_pk_mul_f32 v[126:127], v[126:127], v[128:129]
	s_nop 0
	v_pk_mul_f32 v[124:125], v[124:125], v[126:127]
	v_mul_f32_e32 v126, 0xbfb8aa3b, v118
	v_mul_f32_e32 v127, 0xbfb8aa3b, v119
	v_exp_f32_e32 v126, v126
	v_exp_f32_e32 v127, v127
	v_add_f32_e32 v126, 1.0, v126
	v_add_f32_e32 v127, 1.0, v127
	v_rcp_f32_e32 v126, v126
	v_rcp_f32_e32 v127, v127
	s_nop 0
	v_pk_mul_f32 v[118:119], v[118:119], v[126:127]
	s_nop 0
	v_pk_mul_f32 v[118:119], v[114:115], v[118:119]
	v_pk_fma_f32 v[114:115], v[120:121], v[180:181], v[84:85] op_sel_hi:[1,0,1]
	s_nop 0
	v_mul_f32_e32 v120, 0xbfb8aa3b, v114
	v_mul_f32_e32 v121, 0xbfb8aa3b, v115
	v_exp_f32_e32 v120, v120
	v_exp_f32_e32 v121, v121
	v_add_f32_e32 v120, 1.0, v120
	v_add_f32_e32 v121, 1.0, v121
	v_rcp_f32_e32 v120, v120
	v_rcp_f32_e32 v121, v121
	s_nop 0
	v_pk_mul_f32 v[114:115], v[114:115], v[120:121]
	s_nop 0
	v_pk_mul_f32 v[120:121], v[116:117], v[114:115]
	v_cvt_pk_bf16_f32 v116, v118, v119
	v_lshrrev_b32_e32 v118, 8, v187
	v_mad_i32_i24 v118, v118, 44, v161
	v_ashrrev_i32_e32 v119, 31, v118
	v_cvt_pk_bf16_f32 v117, v120, v121
	v_lshlrev_b64 v[118:119], 15, v[118:119]
	v_lshlrev_b32_e32 v120, 7, v187
	v_lshl_add_u64 v[118:119], s[12:13], 0, v[118:119]
	v_and_b32_e32 v120, 0x7f80, v120
	v_mov_b32_e32 v121, v0
	v_lshl_add_u64 v[118:119], v[118:119], 0, v[120:121]
	v_cvt_pk_bf16_f32 v114, v122, v123
	v_cvt_pk_bf16_f32 v115, v124, v125
	v_lshl_add_u64 v[118:119], v[118:119], 0, v[130:131]
	global_store_dwordx4 v[118:119], v[114:117], off
	v_pk_fma_f32 v[110:111], v[110:111], v[178:179], v[98:99] op_sel_hi:[1,0,1]
	v_pk_fma_f32 v[106:107], v[106:107], v[178:179], v[102:103] op_sel_hi:[1,0,1]
	v_mul_f32_e32 v114, 0xbfb8aa3b, v110
	v_mul_f32_e32 v115, 0xbfb8aa3b, v111
	v_exp_f32_e32 v114, v114
	v_exp_f32_e32 v115, v115
	v_pk_fma_f32 v[108:109], v[108:109], v[178:179], v[104:105] op_sel_hi:[1,0,1]
	v_pk_fma_f32 v[94:95], v[94:95], v[178:179], v[82:83] op_sel_hi:[1,0,1]
	v_add_f32_e32 v114, 1.0, v114
	v_add_f32_e32 v115, 1.0, v115
	v_rcp_f32_e32 v114, v114
	v_rcp_f32_e32 v115, v115
	v_pk_fma_f32 v[90:91], v[90:91], v[178:179], v[86:87] op_sel_hi:[1,0,1]
	v_pk_fma_f32 v[92:93], v[92:93], v[178:179], v[88:89] op_sel_hi:[1,0,1]
	v_pk_mul_f32 v[110:111], v[110:111], v[114:115]
	s_nop 0
	v_pk_mul_f32 v[106:107], v[106:107], v[110:111]
	v_pk_fma_f32 v[110:111], v[112:113], v[178:179], v[100:101] op_sel_hi:[1,0,1]
	s_nop 0
	v_mul_f32_e32 v112, 0xbfb8aa3b, v110
	v_mul_f32_e32 v113, 0xbfb8aa3b, v111
	v_exp_f32_e32 v112, v112
	v_exp_f32_e32 v113, v113
	v_add_f32_e32 v112, 1.0, v112
	v_add_f32_e32 v113, 1.0, v113
	v_rcp_f32_e32 v112, v112
	v_rcp_f32_e32 v113, v113
	s_nop 0
	v_pk_mul_f32 v[110:111], v[110:111], v[112:113]
	s_nop 0
	v_pk_mul_f32 v[108:109], v[108:109], v[110:111]
	v_mul_f32_e32 v110, 0xbfb8aa3b, v94
	v_mul_f32_e32 v111, 0xbfb8aa3b, v95
	v_exp_f32_e32 v110, v110
	v_exp_f32_e32 v111, v111
	v_add_f32_e32 v110, 1.0, v110
	v_add_f32_e32 v111, 1.0, v111
	v_rcp_f32_e32 v110, v110
	v_rcp_f32_e32 v111, v111
	s_nop 0
	v_pk_mul_f32 v[94:95], v[94:95], v[110:111]
	s_nop 0
	v_pk_mul_f32 v[94:95], v[90:91], v[94:95]
	v_pk_fma_f32 v[90:91], v[96:97], v[178:179], v[84:85] op_sel_hi:[1,0,1]
	s_nop 0
	v_mul_f32_e32 v96, 0xbfb8aa3b, v90
	v_mul_f32_e32 v97, 0xbfb8aa3b, v91
	v_exp_f32_e32 v96, v96
	v_exp_f32_e32 v97, v97
	v_add_f32_e32 v96, 1.0, v96
	v_add_f32_e32 v97, 1.0, v97
	v_rcp_f32_e32 v96, v96
	v_rcp_f32_e32 v97, v97
	s_nop 0
	v_pk_mul_f32 v[90:91], v[90:91], v[96:97]
	s_nop 0
	v_pk_mul_f32 v[96:97], v[92:93], v[90:91]
	v_cvt_pk_bf16_f32 v92, v94, v95
	v_lshrrev_b32_e32 v94, 8, v185
	v_mad_i32_i24 v94, v94, 44, v161
	v_ashrrev_i32_e32 v95, 31, v94
	v_cvt_pk_bf16_f32 v93, v96, v97
	v_lshlrev_b64 v[94:95], 15, v[94:95]
	v_lshlrev_b32_e32 v96, 7, v185
	v_lshl_add_u64 v[94:95], s[12:13], 0, v[94:95]
	v_and_b32_e32 v96, 0x7f80, v96
	v_mov_b32_e32 v97, v0
	v_lshl_add_u64 v[94:95], v[94:95], 0, v[96:97]
	v_cvt_pk_bf16_f32 v90, v106, v107
	v_cvt_pk_bf16_f32 v91, v108, v109
	v_lshl_add_u64 v[94:95], v[94:95], 0, v[130:131]
	global_store_dwordx4 v[94:95], v[90:93], off
	v_pk_fma_f32 v[78:79], v[78:79], v[176:177], v[98:99] op_sel_hi:[1,0,1]
	v_pk_fma_f32 v[74:75], v[74:75], v[176:177], v[102:103] op_sel_hi:[1,0,1]
	v_mul_f32_e32 v90, 0xbfb8aa3b, v78
	v_mul_f32_e32 v91, 0xbfb8aa3b, v79
	v_exp_f32_e32 v90, v90
	v_exp_f32_e32 v91, v91
	v_pk_fma_f32 v[76:77], v[76:77], v[176:177], v[104:105] op_sel_hi:[1,0,1]
	v_pk_fma_f32 v[70:71], v[70:71], v[176:177], v[82:83] op_sel_hi:[1,0,1]
	v_add_f32_e32 v90, 1.0, v90
	v_add_f32_e32 v91, 1.0, v91
	v_rcp_f32_e32 v90, v90
	v_rcp_f32_e32 v91, v91
	v_pk_fma_f32 v[66:67], v[66:67], v[176:177], v[86:87] op_sel_hi:[1,0,1]
	v_pk_fma_f32 v[68:69], v[68:69], v[176:177], v[88:89] op_sel_hi:[1,0,1]
	v_pk_mul_f32 v[78:79], v[78:79], v[90:91]
	s_nop 0
	v_pk_mul_f32 v[74:75], v[74:75], v[78:79]
	v_pk_fma_f32 v[78:79], v[80:81], v[176:177], v[100:101] op_sel_hi:[1,0,1]
	s_nop 0
	v_mul_f32_e32 v80, 0xbfb8aa3b, v78
	v_mul_f32_e32 v81, 0xbfb8aa3b, v79
	v_exp_f32_e32 v80, v80
	v_exp_f32_e32 v81, v81
	v_add_f32_e32 v80, 1.0, v80
	v_add_f32_e32 v81, 1.0, v81
	v_rcp_f32_e32 v80, v80
	v_rcp_f32_e32 v81, v81
	s_nop 0
	v_pk_mul_f32 v[78:79], v[78:79], v[80:81]
	s_nop 0
	v_pk_mul_f32 v[76:77], v[76:77], v[78:79]
	v_mul_f32_e32 v78, 0xbfb8aa3b, v70
	v_mul_f32_e32 v79, 0xbfb8aa3b, v71
	v_exp_f32_e32 v78, v78
	v_exp_f32_e32 v79, v79
	v_add_f32_e32 v78, 1.0, v78
	v_add_f32_e32 v79, 1.0, v79
	v_rcp_f32_e32 v78, v78
	v_rcp_f32_e32 v79, v79
	s_nop 0
	v_pk_mul_f32 v[70:71], v[70:71], v[78:79]
	s_nop 0
	v_pk_mul_f32 v[70:71], v[66:67], v[70:71]
	v_pk_fma_f32 v[66:67], v[72:73], v[176:177], v[84:85] op_sel_hi:[1,0,1]
	s_nop 0
	v_mul_f32_e32 v72, 0xbfb8aa3b, v66
	v_mul_f32_e32 v73, 0xbfb8aa3b, v67
	v_exp_f32_e32 v72, v72
	v_exp_f32_e32 v73, v73
	v_add_f32_e32 v72, 1.0, v72
	v_add_f32_e32 v73, 1.0, v73
	v_rcp_f32_e32 v72, v72
	v_rcp_f32_e32 v73, v73
	s_nop 0
	v_pk_mul_f32 v[66:67], v[66:67], v[72:73]
	s_nop 0
	v_pk_mul_f32 v[72:73], v[68:69], v[66:67]
	v_cvt_pk_bf16_f32 v68, v70, v71
	v_lshrrev_b32_e32 v70, 8, v183
	v_mad_i32_i24 v70, v70, 44, v161
	v_ashrrev_i32_e32 v71, 31, v70
	v_cvt_pk_bf16_f32 v69, v72, v73
	v_lshlrev_b64 v[70:71], 15, v[70:71]
	v_lshlrev_b32_e32 v72, 7, v183
	v_lshl_add_u64 v[70:71], s[12:13], 0, v[70:71]
	v_and_b32_e32 v72, 0x7f80, v72
	v_mov_b32_e32 v73, v0
	v_lshl_add_u64 v[70:71], v[70:71], 0, v[72:73]
	v_cvt_pk_bf16_f32 v66, v74, v75
	v_cvt_pk_bf16_f32 v67, v76, v77
	v_lshl_add_u64 v[70:71], v[70:71], 0, v[130:131]
	global_store_dwordx4 v[70:71], v[66:69], off
	v_pk_fma_f32 v[62:63], v[62:63], v[174:175], v[98:99] op_sel_hi:[1,0,1]
	v_pk_fma_f32 v[58:59], v[58:59], v[174:175], v[102:103] op_sel_hi:[1,0,1]
	v_mul_f32_e32 v66, 0xbfb8aa3b, v62
	v_mul_f32_e32 v67, 0xbfb8aa3b, v63
	v_exp_f32_e32 v66, v66
	v_exp_f32_e32 v67, v67
	v_pk_fma_f32 v[60:61], v[60:61], v[174:175], v[104:105] op_sel_hi:[1,0,1]
	v_pk_fma_f32 v[54:55], v[54:55], v[174:175], v[82:83] op_sel_hi:[1,0,1]
	v_add_f32_e32 v66, 1.0, v66
	v_add_f32_e32 v67, 1.0, v67
	v_rcp_f32_e32 v66, v66
	v_rcp_f32_e32 v67, v67
	v_pk_fma_f32 v[50:51], v[50:51], v[174:175], v[86:87] op_sel_hi:[1,0,1]
	v_pk_fma_f32 v[52:53], v[52:53], v[174:175], v[88:89] op_sel_hi:[1,0,1]
	v_pk_mul_f32 v[62:63], v[62:63], v[66:67]
	s_nop 0
	v_pk_mul_f32 v[58:59], v[58:59], v[62:63]
	v_pk_fma_f32 v[62:63], v[64:65], v[174:175], v[100:101] op_sel_hi:[1,0,1]
	s_nop 0
	v_mul_f32_e32 v64, 0xbfb8aa3b, v62
	v_mul_f32_e32 v65, 0xbfb8aa3b, v63
	v_exp_f32_e32 v64, v64
	v_exp_f32_e32 v65, v65
	v_add_f32_e32 v64, 1.0, v64
	v_add_f32_e32 v65, 1.0, v65
	v_rcp_f32_e32 v64, v64
	v_rcp_f32_e32 v65, v65
	s_nop 0
	v_pk_mul_f32 v[62:63], v[62:63], v[64:65]
	s_nop 0
	v_pk_mul_f32 v[60:61], v[60:61], v[62:63]
	v_mul_f32_e32 v62, 0xbfb8aa3b, v54
	v_mul_f32_e32 v63, 0xbfb8aa3b, v55
	v_exp_f32_e32 v62, v62
	v_exp_f32_e32 v63, v63
	v_add_f32_e32 v62, 1.0, v62
	v_add_f32_e32 v63, 1.0, v63
	v_rcp_f32_e32 v62, v62
	v_rcp_f32_e32 v63, v63
	s_nop 0
	v_pk_mul_f32 v[54:55], v[54:55], v[62:63]
	s_nop 0
	v_pk_mul_f32 v[54:55], v[50:51], v[54:55]
	v_pk_fma_f32 v[50:51], v[56:57], v[174:175], v[84:85] op_sel_hi:[1,0,1]
	s_nop 0
	v_mul_f32_e32 v56, 0xbfb8aa3b, v50
	v_mul_f32_e32 v57, 0xbfb8aa3b, v51
	v_exp_f32_e32 v56, v56
	v_exp_f32_e32 v57, v57
	v_add_f32_e32 v56, 1.0, v56
	v_add_f32_e32 v57, 1.0, v57
	v_rcp_f32_e32 v56, v56
	v_rcp_f32_e32 v57, v57
	s_nop 0
	v_pk_mul_f32 v[50:51], v[50:51], v[56:57]
	s_nop 0
	v_pk_mul_f32 v[56:57], v[52:53], v[50:51]
	v_cvt_pk_bf16_f32 v52, v54, v55
	v_lshrrev_b32_e32 v54, 8, v181
	v_mad_i32_i24 v54, v54, 44, v161
	v_ashrrev_i32_e32 v55, 31, v54
	v_cvt_pk_bf16_f32 v53, v56, v57
	v_lshlrev_b64 v[54:55], 15, v[54:55]
	v_lshlrev_b32_e32 v56, 7, v181
	v_lshl_add_u64 v[54:55], s[12:13], 0, v[54:55]
	v_and_b32_e32 v56, 0x7f80, v56
	v_mov_b32_e32 v57, v0
	v_lshl_add_u64 v[54:55], v[54:55], 0, v[56:57]
	v_cvt_pk_bf16_f32 v50, v58, v59
	v_cvt_pk_bf16_f32 v51, v60, v61
	v_lshl_add_u64 v[54:55], v[54:55], 0, v[130:131]
	global_store_dwordx4 v[54:55], v[50:53], off
	v_pk_fma_f32 v[46:47], v[46:47], v[172:173], v[98:99] op_sel_hi:[1,0,1]
	v_pk_fma_f32 v[42:43], v[42:43], v[172:173], v[102:103] op_sel_hi:[1,0,1]
	v_mul_f32_e32 v50, 0xbfb8aa3b, v46
	v_mul_f32_e32 v51, 0xbfb8aa3b, v47
	v_exp_f32_e32 v50, v50
	v_exp_f32_e32 v51, v51
	v_pk_fma_f32 v[44:45], v[44:45], v[172:173], v[104:105] op_sel_hi:[1,0,1]
	v_pk_fma_f32 v[38:39], v[38:39], v[172:173], v[82:83] op_sel_hi:[1,0,1]
	v_add_f32_e32 v50, 1.0, v50
	v_add_f32_e32 v51, 1.0, v51
	v_rcp_f32_e32 v50, v50
	v_rcp_f32_e32 v51, v51
	v_pk_fma_f32 v[34:35], v[34:35], v[172:173], v[86:87] op_sel_hi:[1,0,1]
	v_pk_fma_f32 v[36:37], v[36:37], v[172:173], v[88:89] op_sel_hi:[1,0,1]
	v_pk_mul_f32 v[46:47], v[46:47], v[50:51]
	s_nop 0
	v_pk_mul_f32 v[42:43], v[42:43], v[46:47]
	v_pk_fma_f32 v[46:47], v[48:49], v[172:173], v[100:101] op_sel_hi:[1,0,1]
	s_nop 0
	v_mul_f32_e32 v48, 0xbfb8aa3b, v46
	v_mul_f32_e32 v49, 0xbfb8aa3b, v47
	v_exp_f32_e32 v48, v48
	v_exp_f32_e32 v49, v49
	v_add_f32_e32 v48, 1.0, v48
	v_add_f32_e32 v49, 1.0, v49
	v_rcp_f32_e32 v48, v48
	v_rcp_f32_e32 v49, v49
	s_nop 0
	v_pk_mul_f32 v[46:47], v[46:47], v[48:49]
	s_nop 0
	v_pk_mul_f32 v[44:45], v[44:45], v[46:47]
	v_mul_f32_e32 v46, 0xbfb8aa3b, v38
	v_mul_f32_e32 v47, 0xbfb8aa3b, v39
	v_exp_f32_e32 v46, v46
	v_exp_f32_e32 v47, v47
	v_add_f32_e32 v46, 1.0, v46
	v_add_f32_e32 v47, 1.0, v47
	v_rcp_f32_e32 v46, v46
	v_rcp_f32_e32 v47, v47
	s_nop 0
	v_pk_mul_f32 v[38:39], v[38:39], v[46:47]
	s_nop 0
	v_pk_mul_f32 v[38:39], v[34:35], v[38:39]
	v_pk_fma_f32 v[34:35], v[40:41], v[172:173], v[84:85] op_sel_hi:[1,0,1]
	s_nop 0
	v_mul_f32_e32 v40, 0xbfb8aa3b, v34
	v_mul_f32_e32 v41, 0xbfb8aa3b, v35
	v_exp_f32_e32 v40, v40
	v_exp_f32_e32 v41, v41
	v_add_f32_e32 v40, 1.0, v40
	v_add_f32_e32 v41, 1.0, v41
	v_rcp_f32_e32 v40, v40
	v_rcp_f32_e32 v41, v41
	s_nop 0
	v_pk_mul_f32 v[34:35], v[34:35], v[40:41]
	s_nop 0
	v_pk_mul_f32 v[40:41], v[36:37], v[34:35]
	v_cvt_pk_bf16_f32 v36, v38, v39
	v_lshrrev_b32_e32 v38, 8, v179
	v_mad_i32_i24 v38, v38, 44, v161
	v_ashrrev_i32_e32 v39, 31, v38
	v_cvt_pk_bf16_f32 v37, v40, v41
	v_lshlrev_b64 v[38:39], 15, v[38:39]
	v_lshlrev_b32_e32 v40, 7, v179
	v_lshl_add_u64 v[38:39], s[12:13], 0, v[38:39]
	v_and_b32_e32 v40, 0x7f80, v40
	v_mov_b32_e32 v41, v0
	v_lshl_add_u64 v[38:39], v[38:39], 0, v[40:41]
	v_cvt_pk_bf16_f32 v34, v42, v43
	v_cvt_pk_bf16_f32 v35, v44, v45
	v_lshl_add_u64 v[38:39], v[38:39], 0, v[130:131]
	global_store_dwordx4 v[38:39], v[34:37], off
	v_pk_fma_f32 v[30:31], v[30:31], v[158:159], v[98:99] op_sel_hi:[1,0,1]
	v_pk_fma_f32 v[26:27], v[26:27], v[158:159], v[102:103] op_sel_hi:[1,0,1]
	v_mul_f32_e32 v34, 0xbfb8aa3b, v30
	v_mul_f32_e32 v35, 0xbfb8aa3b, v31
	v_exp_f32_e32 v34, v34
	v_exp_f32_e32 v35, v35
	v_pk_fma_f32 v[28:29], v[28:29], v[158:159], v[104:105] op_sel_hi:[1,0,1]
	v_pk_fma_f32 v[22:23], v[22:23], v[158:159], v[82:83] op_sel_hi:[1,0,1]
	v_add_f32_e32 v34, 1.0, v34
	v_add_f32_e32 v35, 1.0, v35
	v_rcp_f32_e32 v34, v34
	v_rcp_f32_e32 v35, v35
	v_pk_fma_f32 v[18:19], v[18:19], v[158:159], v[86:87] op_sel_hi:[1,0,1]
	v_pk_fma_f32 v[20:21], v[20:21], v[158:159], v[88:89] op_sel_hi:[1,0,1]
	v_pk_mul_f32 v[30:31], v[30:31], v[34:35]
	s_nop 0
	v_pk_mul_f32 v[26:27], v[26:27], v[30:31]
	v_pk_fma_f32 v[30:31], v[32:33], v[158:159], v[100:101] op_sel_hi:[1,0,1]
	s_nop 0
	v_mul_f32_e32 v32, 0xbfb8aa3b, v30
	v_mul_f32_e32 v33, 0xbfb8aa3b, v31
	v_exp_f32_e32 v32, v32
	v_exp_f32_e32 v33, v33
	v_add_f32_e32 v32, 1.0, v32
	v_add_f32_e32 v33, 1.0, v33
	v_rcp_f32_e32 v32, v32
	v_rcp_f32_e32 v33, v33
	s_nop 0
	v_pk_mul_f32 v[30:31], v[30:31], v[32:33]
	s_nop 0
	v_pk_mul_f32 v[28:29], v[28:29], v[30:31]
	v_mul_f32_e32 v30, 0xbfb8aa3b, v22
	v_mul_f32_e32 v31, 0xbfb8aa3b, v23
	v_exp_f32_e32 v30, v30
	v_exp_f32_e32 v31, v31
	v_add_f32_e32 v30, 1.0, v30
	v_add_f32_e32 v31, 1.0, v31
	v_rcp_f32_e32 v30, v30
	v_rcp_f32_e32 v31, v31
	s_nop 0
	v_pk_mul_f32 v[22:23], v[22:23], v[30:31]
	s_nop 0
	v_pk_mul_f32 v[22:23], v[18:19], v[22:23]
	v_pk_fma_f32 v[18:19], v[24:25], v[158:159], v[84:85] op_sel_hi:[1,0,1]
	s_nop 0
	v_mul_f32_e32 v24, 0xbfb8aa3b, v18
	v_mul_f32_e32 v25, 0xbfb8aa3b, v19
	v_exp_f32_e32 v24, v24
	v_exp_f32_e32 v25, v25
	v_add_f32_e32 v24, 1.0, v24
	v_add_f32_e32 v25, 1.0, v25
	v_rcp_f32_e32 v24, v24
	v_rcp_f32_e32 v25, v25
	s_nop 0
	v_pk_mul_f32 v[18:19], v[18:19], v[24:25]
	s_nop 0
	v_pk_mul_f32 v[24:25], v[20:21], v[18:19]
	v_cvt_pk_bf16_f32 v20, v22, v23
	v_lshrrev_b32_e32 v22, 8, v177
	v_mad_i32_i24 v22, v22, 44, v161
	v_ashrrev_i32_e32 v23, 31, v22
	v_cvt_pk_bf16_f32 v21, v24, v25
	v_lshlrev_b64 v[22:23], 15, v[22:23]
	v_lshlrev_b32_e32 v24, 7, v177
	v_lshl_add_u64 v[22:23], s[12:13], 0, v[22:23]
	v_and_b32_e32 v24, 0x7f80, v24
	v_mov_b32_e32 v25, v0
	v_lshl_add_u64 v[22:23], v[22:23], 0, v[24:25]
	v_cvt_pk_bf16_f32 v18, v26, v27
	v_cvt_pk_bf16_f32 v19, v28, v29
	v_lshl_add_u64 v[22:23], v[22:23], 0, v[130:131]
	global_store_dwordx4 v[22:23], v[18:21], off
	v_pk_fma_f32 v[14:15], v[14:15], v[160:161], v[98:99] op_sel_hi:[1,0,1]
	v_pk_fma_f32 v[10:11], v[10:11], v[160:161], v[102:103] op_sel_hi:[1,0,1]
	v_mul_f32_e32 v18, 0xbfb8aa3b, v14
	v_mul_f32_e32 v19, 0xbfb8aa3b, v15
	v_exp_f32_e32 v18, v18
	v_exp_f32_e32 v19, v19
	v_pk_fma_f32 v[12:13], v[12:13], v[160:161], v[104:105] op_sel_hi:[1,0,1]
	v_pk_fma_f32 v[6:7], v[6:7], v[160:161], v[82:83] op_sel_hi:[1,0,1]
	v_add_f32_e32 v18, 1.0, v18
	v_add_f32_e32 v19, 1.0, v19
	v_rcp_f32_e32 v18, v18
	v_rcp_f32_e32 v19, v19
	v_pk_fma_f32 v[2:3], v[2:3], v[160:161], v[86:87] op_sel_hi:[1,0,1]
	v_pk_fma_f32 v[4:5], v[4:5], v[160:161], v[88:89] op_sel_hi:[1,0,1]
	s_and_b64 vcc, exec, s[36:37]
	v_pk_mul_f32 v[14:15], v[14:15], v[18:19]
	s_mov_b32 s38, s2
	v_pk_mul_f32 v[10:11], v[10:11], v[14:15]
	v_pk_fma_f32 v[14:15], v[16:17], v[160:161], v[100:101] op_sel_hi:[1,0,1]
	s_mov_b32 s10, s4
	v_mul_f32_e32 v16, 0xbfb8aa3b, v14
	v_mul_f32_e32 v17, 0xbfb8aa3b, v15
	v_exp_f32_e32 v16, v16
	v_exp_f32_e32 v17, v17
	s_mov_b64 s[14:15], s[8:9]
	v_add_f32_e32 v16, 1.0, v16
	v_add_f32_e32 v17, 1.0, v17
	v_rcp_f32_e32 v16, v16
	v_rcp_f32_e32 v17, v17
	s_nop 0
	v_pk_mul_f32 v[14:15], v[14:15], v[16:17]
	s_nop 0
	v_pk_mul_f32 v[12:13], v[12:13], v[14:15]
	v_mul_f32_e32 v14, 0xbfb8aa3b, v6
	v_mul_f32_e32 v15, 0xbfb8aa3b, v7
	v_exp_f32_e32 v14, v14
	v_exp_f32_e32 v15, v15
	v_add_f32_e32 v14, 1.0, v14
	v_add_f32_e32 v15, 1.0, v15
	v_rcp_f32_e32 v14, v14
	v_rcp_f32_e32 v15, v15
	s_nop 0
	v_pk_mul_f32 v[6:7], v[6:7], v[14:15]
	s_nop 0
	v_pk_mul_f32 v[6:7], v[2:3], v[6:7]
	v_pk_fma_f32 v[2:3], v[8:9], v[160:161], v[84:85] op_sel_hi:[1,0,1]
	s_nop 0
	v_mul_f32_e32 v8, 0xbfb8aa3b, v2
	v_mul_f32_e32 v9, 0xbfb8aa3b, v3
	v_exp_f32_e32 v8, v8
	v_exp_f32_e32 v9, v9
	v_add_f32_e32 v8, 1.0, v8
	v_add_f32_e32 v9, 1.0, v9
	v_rcp_f32_e32 v8, v8
	v_rcp_f32_e32 v9, v9
	s_nop 0
	v_pk_mul_f32 v[2:3], v[2:3], v[8:9]
	s_nop 0
	v_pk_mul_f32 v[8:9], v[4:5], v[2:3]
	v_cvt_pk_bf16_f32 v4, v6, v7
	v_lshrrev_b32_e32 v6, 8, v175
	v_mad_i32_i24 v6, v6, 44, v161
	v_ashrrev_i32_e32 v7, 31, v6
	v_cvt_pk_bf16_f32 v5, v8, v9
	v_lshlrev_b64 v[6:7], 15, v[6:7]
	v_lshlrev_b32_e32 v8, 7, v175
	v_lshl_add_u64 v[6:7], s[12:13], 0, v[6:7]
	v_and_b32_e32 v8, 0x7f80, v8
	v_mov_b32_e32 v9, v0
	v_lshl_add_u64 v[6:7], v[6:7], 0, v[8:9]
	v_cvt_pk_bf16_f32 v2, v10, v11
	v_cvt_pk_bf16_f32 v3, v12, v13
	v_lshl_add_u64 v[6:7], v[6:7], 0, v[130:131]
	s_mov_b64 s[12:13], s[6:7]
	global_store_dwordx4 v[6:7], v[2:5], off
	s_cbranch_vccnz .LBB0_875
